# first-group fragment reads reordered with per-MFMA counted waits so the first MFMA starts after two reads
# speedup vs baseline: 1.0065x; 1.0065x over previous
; #define MFMA16(a, b, c) __builtin_amdgcn_mfma_f32_16x16x32_bf16((a), (b), (c), 0, 0, 0)
;     ...
;   for (int kt = 0; kt < nk; ++kt) {
;     const int buf = kt & 1;
;     const char* cA = smem + buf * STAGE + (wm * 32 * MI + r16) * 128;
;     const char* cB = smem + buf * STAGE + 32768 + (wn * 64 + r16) * 128;
; #pragma unroll
;     for (int k2 = 0; k2 < 2; ++k2) {
;       if (k2 == 1 && kt + 1 < nk) STAGE_TILE(buf ^ 1, (kt + 1) * 64)
;       const int po = ((4 * k2 + q4) ^ swz) * 16;
;       bf16x8 bf[4];
; #pragma unroll
;       for (int nt = 0; nt < 4; ++nt) bf[nt] = *(const bf16x8*)(cB + nt * 16 * 128 + po);
;       bf16x8 afc = *(const bf16x8*)(cA + po);
; #pragma unroll
;       for (int a = 0; a < MT; ++a) {
;         bf16x8 afn = afc;
;         if (a + 1 < MT) afn = *(const bf16x8*)(cA + (a + 1) * 16 * 128 + po);
;         __builtin_amdgcn_sched_barrier(0);
; #pragma unroll
;         for (int nt = 0; nt < 4; ++nt) acc[a][nt] = MFMA16(bf[nt], afc, acc[a][nt]);
;         __builtin_amdgcn_sched_barrier(0);
;         afc = afn;
;       }
;     }
;     asm volatile("s_waitcnt vmcnt(0)" ::: "memory");
;     __syncthreads();
;   }
.LBB0_48:
	s_and_b32 s42, s41, 0x10000
	s_add_i32 s43, s42, 0
	s_xor_b32 s42, s42, 0x10000
	v_add_u32_e32 v174, s43, v147
	v_add_u32_e32 v162, v174, v146
	v_add_u32_e32 v149, s43, v148
	v_add_u32_e32 v175, v149, v146
	ds_read_b128 v[150:153], v162 offset:32768
	ds_read_b128 v[166:169], v175
	ds_read_b128 v[154:157], v162 offset:34816
	ds_read_b128 v[158:161], v162 offset:36864
	ds_read_b128 v[162:165], v162 offset:38912
	ds_read_b128 v[170:173], v175 offset:2048
	s_waitcnt lgkmcnt(4)
	v_mfma_f32_16x16x32_bf16 v[126:129], v[150:153], v[166:169], v[126:129]
	v_readfirstlane_b32 s43, v145
	s_waitcnt lgkmcnt(3)
	v_mfma_f32_16x16x32_bf16 v[122:125], v[154:157], v[166:169], v[122:125]
	s_nop 0
	s_waitcnt lgkmcnt(2)
	v_mfma_f32_16x16x32_bf16 v[118:121], v[158:161], v[166:169], v[118:121]
	s_add_u32 s43, s43, s42
	s_waitcnt lgkmcnt(1)
	v_mfma_f32_16x16x32_bf16 v[114:117], v[162:165], v[166:169], v[114:117]
	ds_read_b128 v[166:169], v175 offset:4096
	s_add_u32 m0, s43, 0x0
	s_waitcnt lgkmcnt(1)
	v_mfma_f32_16x16x32_bf16 v[110:113], v[150:153], v[170:173], v[110:113]
	global_load_lds_dwordx4 v176, s[100:101]
	v_mfma_f32_16x16x32_bf16 v[106:109], v[154:157], v[170:173], v[106:109]
	s_add_u32 m0, s43, 0x2000
	v_mfma_f32_16x16x32_bf16 v[102:105], v[158:161], v[170:173], v[102:105]
	global_load_lds_dwordx4 v177, s[100:101]
	v_mfma_f32_16x16x32_bf16 v[98:101], v[162:165], v[170:173], v[98:101]
	ds_read_b128 v[170:173], v175 offset:6144
	s_add_u32 m0, s43, 0x4000
	s_waitcnt lgkmcnt(1)
	v_mfma_f32_16x16x32_bf16 v[94:97], v[150:153], v[166:169], v[94:97]
	global_load_lds_dwordx4 v178, s[100:101]
	v_mfma_f32_16x16x32_bf16 v[90:93], v[154:157], v[166:169], v[90:93]
	s_add_u32 m0, s43, 0x6000
	v_mfma_f32_16x16x32_bf16 v[86:89], v[158:161], v[166:169], v[86:89]
	global_load_lds_dwordx4 v179, s[100:101]
	v_mfma_f32_16x16x32_bf16 v[82:85], v[162:165], v[166:169], v[82:85]
	ds_read_b128 v[166:169], v175 offset:8192
	s_add_u32 m0, s43, 0x8000
	s_waitcnt lgkmcnt(1)
	v_mfma_f32_16x16x32_bf16 v[78:81], v[150:153], v[170:173], v[78:81]
	global_load_lds_dwordx4 v180, s[100:101]
	v_mfma_f32_16x16x32_bf16 v[74:77], v[154:157], v[170:173], v[74:77]
	s_add_u32 m0, s43, 0xa000
	v_mfma_f32_16x16x32_bf16 v[70:73], v[158:161], v[170:173], v[70:73]
	global_load_lds_dwordx4 v181, s[100:101]
	v_mfma_f32_16x16x32_bf16 v[66:69], v[162:165], v[170:173], v[66:69]
	ds_read_b128 v[170:173], v175 offset:10240
	s_add_u32 m0, s43, 0xc000
	s_waitcnt lgkmcnt(1)
	v_mfma_f32_16x16x32_bf16 v[62:65], v[150:153], v[166:169], v[62:65]
	global_load_lds_dwordx4 v182, s[100:101]
	v_mfma_f32_16x16x32_bf16 v[58:61], v[154:157], v[166:169], v[58:61]
	s_add_u32 m0, s43, 0xe000
	v_mfma_f32_16x16x32_bf16 v[54:57], v[158:161], v[166:169], v[54:57]
	global_load_lds_dwordx4 v183, s[100:101]
	v_mfma_f32_16x16x32_bf16 v[50:53], v[162:165], v[166:169], v[50:53]
	ds_read_b128 v[166:169], v175 offset:12288
	v_add_u32_e32 v203, v174, v144
	s_waitcnt lgkmcnt(1)
	v_mfma_f32_16x16x32_bf16 v[46:49], v[150:153], v[170:173], v[46:49]
	v_add_u32_e32 v192, v149, v144
	v_mfma_f32_16x16x32_bf16 v[42:45], v[154:157], v[170:173], v[42:45]
	ds_read_b128 v[204:207], v203 offset:32768
	v_mfma_f32_16x16x32_bf16 v[38:41], v[158:161], v[170:173], v[38:41]
	ds_read_b128 v[208:211], v203 offset:34816
	v_mfma_f32_16x16x32_bf16 v[34:37], v[162:165], v[170:173], v[34:37]
	ds_read_b128 v[170:173], v175 offset:14336
	ds_read_b128 v[212:215], v203 offset:36864
	s_waitcnt lgkmcnt(4)
	v_mfma_f32_16x16x32_bf16 v[30:33], v[150:153], v[166:169], v[30:33]
	ds_read_b128 v[216:219], v203 offset:38912
	v_mfma_f32_16x16x32_bf16 v[26:29], v[154:157], v[166:169], v[26:29]
	ds_read_b128 v[220:223], v192
	v_mfma_f32_16x16x32_bf16 v[22:25], v[158:161], v[166:169], v[22:25]
	ds_read_b128 v[198:201], v192 offset:2048
	v_mfma_f32_16x16x32_bf16 v[18:21], v[162:165], v[166:169], v[18:21]
	s_waitcnt lgkmcnt(4)
	v_mfma_f32_16x16x32_bf16 v[14:17], v[150:153], v[170:173], v[14:17]
	v_mfma_f32_16x16x32_bf16 v[10:13], v[154:157], v[170:173], v[10:13]
	v_mfma_f32_16x16x32_bf16 v[6:9], v[158:161], v[170:173], v[6:9]
	v_mfma_f32_16x16x32_bf16 v[2:5], v[162:165], v[170:173], v[2:5]
	s_waitcnt lgkmcnt(1)
	v_mfma_f32_16x16x32_bf16 v[126:129], v[204:207], v[220:223], v[126:129]
	s_add_u32 s100, s100, 0x80
	v_mfma_f32_16x16x32_bf16 v[122:125], v[208:211], v[220:223], v[122:125]
	s_addc_u32 s101, s101, 0
	v_mfma_f32_16x16x32_bf16 v[118:121], v[212:215], v[220:223], v[118:121]
	s_add_u32 s16, s16, 0x80
	v_mfma_f32_16x16x32_bf16 v[114:117], v[216:219], v[220:223], v[114:117]
	ds_read_b128 v[220:223], v192 offset:4096
	s_waitcnt lgkmcnt(1)
	v_mfma_f32_16x16x32_bf16 v[110:113], v[204:207], v[198:201], v[110:113]
	s_addc_u32 s17, s17, 0
	v_mfma_f32_16x16x32_bf16 v[106:109], v[208:211], v[198:201], v[106:109]
	s_add_i32 s41, s41, 0x10000
	v_mfma_f32_16x16x32_bf16 v[102:105], v[212:215], v[198:201], v[102:105]
	v_mfma_f32_16x16x32_bf16 v[98:101], v[216:219], v[198:201], v[98:101]
	ds_read_b128 v[198:201], v192 offset:6144
	s_waitcnt lgkmcnt(1)
	v_mfma_f32_16x16x32_bf16 v[94:97], v[204:207], v[220:223], v[94:97]
	v_mfma_f32_16x16x32_bf16 v[90:93], v[208:211], v[220:223], v[90:93]
	v_mfma_f32_16x16x32_bf16 v[86:89], v[212:215], v[220:223], v[86:89]
	v_mfma_f32_16x16x32_bf16 v[82:85], v[216:219], v[220:223], v[82:85]
	ds_read_b128 v[220:223], v192 offset:8192
	s_waitcnt lgkmcnt(1)
	v_mfma_f32_16x16x32_bf16 v[78:81], v[204:207], v[198:201], v[78:81]
	v_mfma_f32_16x16x32_bf16 v[74:77], v[208:211], v[198:201], v[74:77]
	v_mfma_f32_16x16x32_bf16 v[70:73], v[212:215], v[198:201], v[70:73]
	v_mfma_f32_16x16x32_bf16 v[66:69], v[216:219], v[198:201], v[66:69]
	ds_read_b128 v[198:201], v192 offset:10240
	s_waitcnt lgkmcnt(1)
	v_mfma_f32_16x16x32_bf16 v[62:65], v[204:207], v[220:223], v[62:65]
	v_mfma_f32_16x16x32_bf16 v[58:61], v[208:211], v[220:223], v[58:61]
	v_mfma_f32_16x16x32_bf16 v[54:57], v[212:215], v[220:223], v[54:57]
	v_mfma_f32_16x16x32_bf16 v[50:53], v[216:219], v[220:223], v[50:53]
	ds_read_b128 v[220:223], v192 offset:12288
	s_waitcnt lgkmcnt(1)
	v_mfma_f32_16x16x32_bf16 v[46:49], v[204:207], v[198:201], v[46:49]
	v_mfma_f32_16x16x32_bf16 v[42:45], v[208:211], v[198:201], v[42:45]
	v_mfma_f32_16x16x32_bf16 v[38:41], v[212:215], v[198:201], v[38:41]
	v_mfma_f32_16x16x32_bf16 v[34:37], v[216:219], v[198:201], v[34:37]
	ds_read_b128 v[198:201], v192 offset:14336
	s_waitcnt lgkmcnt(1)
	v_mfma_f32_16x16x32_bf16 v[30:33], v[204:207], v[220:223], v[30:33]
	v_mfma_f32_16x16x32_bf16 v[26:29], v[208:211], v[220:223], v[26:29]
	v_mfma_f32_16x16x32_bf16 v[22:25], v[212:215], v[220:223], v[22:25]
	v_mfma_f32_16x16x32_bf16 v[18:21], v[216:219], v[220:223], v[18:21]
	s_waitcnt lgkmcnt(0)
	v_mfma_f32_16x16x32_bf16 v[14:17], v[204:207], v[198:201], v[14:17]
	v_mfma_f32_16x16x32_bf16 v[10:13], v[208:211], v[198:201], v[10:13]
	v_mfma_f32_16x16x32_bf16 v[6:9], v[212:215], v[198:201], v[6:9]
	v_mfma_f32_16x16x32_bf16 v[2:5], v[216:219], v[198:201], v[2:5]
	s_cmpk_eq_i32 s16, 0x1580
	s_waitcnt vmcnt(0)
	s_barrier
; #define MFMA16(a, b, c) __builtin_amdgcn_mfma_f32_16x16x32_bf16((a), (b), (c), 0, 0, 0)
;     ...
;   for (int kt = 0; kt < nk; ++kt) {
;     const int buf = kt & 1;
;     const char* cA = smem + buf * STAGE + (wm * 32 * MI + r16) * 128;
;     const char* cB = smem + buf * STAGE + 32768 + (wn * 64 + r16) * 128;
; #pragma unroll
;     for (int k2 = 0; k2 < 2; ++k2) {
;       if (k2 == 1 && kt + 1 < nk) STAGE_TILE(buf ^ 1, (kt + 1) * 64)
;       const int po = ((4 * k2 + q4) ^ swz) * 16;
;       bf16x8 bf[4];
; #pragma unroll
;       for (int nt = 0; nt < 4; ++nt) bf[nt] = *(const bf16x8*)(cB + nt * 16 * 128 + po);
;       bf16x8 afc = *(const bf16x8*)(cA + po);
; #pragma unroll
;       for (int a = 0; a < MT; ++a) {
;         bf16x8 afn = afc;
;         if (a + 1 < MT) afn = *(const bf16x8*)(cA + (a + 1) * 16 * 128 + po);
;         __builtin_amdgcn_sched_barrier(0);
; #pragma unroll
;         for (int nt = 0; nt < 4; ++nt) acc[a][nt] = MFMA16(bf[nt], afc, acc[a][nt]);
;         __builtin_amdgcn_sched_barrier(0);
;         afc = afn;
;       }
;     }
;     asm volatile("s_waitcnt vmcnt(0)" ::: "memory");
;     __syncthreads();
;   }
	s_cbranch_scc0 .LBB0_48
	s_add_i32 s16, 0, 0x10000
	v_add_u32_e32 v138, s16, v148
	v_readlane_b32 s16, v254, 18
	s_nop 1
	v_add_u32_e32 v139, s16, v147
	v_add_u32_e32 v145, v139, v146
	ds_read_b128 v[130:133], v145
	ds_read_b128 v[134:137], v145 offset:2048
	ds_read_b128 v[148:151], v145 offset:4096
	ds_read_b128 v[152:155], v145 offset:6144
	v_add_u32_e32 v145, v138, v146
	ds_read_b128 v[156:159], v145
	ds_read_b128 v[160:163], v145 offset:2048
	s_waitcnt lgkmcnt(1)
	v_mfma_f32_16x16x32_bf16 v[126:129], v[130:133], v[156:159], v[126:129]
	v_mfma_f32_16x16x32_bf16 v[122:125], v[134:137], v[156:159], v[122:125]
	v_mfma_f32_16x16x32_bf16 v[118:121], v[148:151], v[156:159], v[118:121]
	v_mfma_f32_16x16x32_bf16 v[114:117], v[152:155], v[156:159], v[114:117]
	ds_read_b128 v[156:159], v145 offset:4096
	s_waitcnt lgkmcnt(1)
	v_mfma_f32_16x16x32_bf16 v[110:113], v[130:133], v[160:163], v[110:113]
	v_mfma_f32_16x16x32_bf16 v[106:109], v[134:137], v[160:163], v[106:109]
	v_mfma_f32_16x16x32_bf16 v[102:105], v[148:151], v[160:163], v[102:105]
	v_mfma_f32_16x16x32_bf16 v[98:101], v[152:155], v[160:163], v[98:101]
	ds_read_b128 v[160:163], v145 offset:6144
	s_waitcnt lgkmcnt(1)
	v_mfma_f32_16x16x32_bf16 v[94:97], v[130:133], v[156:159], v[94:97]
	v_mfma_f32_16x16x32_bf16 v[90:93], v[134:137], v[156:159], v[90:93]
	v_mfma_f32_16x16x32_bf16 v[86:89], v[148:151], v[156:159], v[86:89]
	v_mfma_f32_16x16x32_bf16 v[82:85], v[152:155], v[156:159], v[82:85]
	ds_read_b128 v[156:159], v145 offset:8192
	s_waitcnt lgkmcnt(1)
	v_mfma_f32_16x16x32_bf16 v[78:81], v[130:133], v[160:163], v[78:81]
	v_mfma_f32_16x16x32_bf16 v[74:77], v[134:137], v[160:163], v[74:77]
	v_mfma_f32_16x16x32_bf16 v[70:73], v[148:151], v[160:163], v[70:73]
	v_mfma_f32_16x16x32_bf16 v[66:69], v[152:155], v[160:163], v[66:69]
	ds_read_b128 v[160:163], v145 offset:10240
	s_waitcnt lgkmcnt(1)
	v_mfma_f32_16x16x32_bf16 v[62:65], v[130:133], v[156:159], v[62:65]
	v_mfma_f32_16x16x32_bf16 v[58:61], v[134:137], v[156:159], v[58:61]
	v_mfma_f32_16x16x32_bf16 v[54:57], v[148:151], v[156:159], v[54:57]
	v_mfma_f32_16x16x32_bf16 v[50:53], v[152:155], v[156:159], v[50:53]
	ds_read_b128 v[156:159], v145 offset:12288
	s_waitcnt lgkmcnt(1)
	v_mfma_f32_16x16x32_bf16 v[46:49], v[130:133], v[160:163], v[46:49]
	v_mfma_f32_16x16x32_bf16 v[42:45], v[134:137], v[160:163], v[42:45]
	v_mfma_f32_16x16x32_bf16 v[38:41], v[148:151], v[160:163], v[38:41]
	v_mfma_f32_16x16x32_bf16 v[34:37], v[152:155], v[160:163], v[34:37]
	ds_read_b128 v[160:163], v145 offset:14336
	s_waitcnt lgkmcnt(1)
	v_mfma_f32_16x16x32_bf16 v[30:33], v[130:133], v[156:159], v[30:33]
	v_mfma_f32_16x16x32_bf16 v[26:29], v[134:137], v[156:159], v[26:29]
	v_mfma_f32_16x16x32_bf16 v[22:25], v[148:151], v[156:159], v[22:25]
	v_mfma_f32_16x16x32_bf16 v[18:21], v[152:155], v[156:159], v[18:21]
	s_waitcnt lgkmcnt(0)
	v_mfma_f32_16x16x32_bf16 v[14:17], v[130:133], v[160:163], v[14:17]
	v_mfma_f32_16x16x32_bf16 v[10:13], v[134:137], v[160:163], v[10:13]
	v_mfma_f32_16x16x32_bf16 v[6:9], v[148:151], v[160:163], v[6:9]
	v_mfma_f32_16x16x32_bf16 v[2:5], v[152:155], v[160:163], v[2:5]
	v_add_u32_e32 v139, v139, v144
	ds_read_b128 v[130:133], v139
	ds_read_b128 v[134:137], v139 offset:2048
	ds_read_b128 v[146:149], v139 offset:4096
	ds_read_b128 v[150:153], v139 offset:6144
	v_add_u32_e32 v138, v138, v144
	ds_read_b128 v[154:157], v138
	ds_read_b128 v[158:161], v138 offset:2048
	s_waitcnt lgkmcnt(1)
	v_mfma_f32_16x16x32_bf16 v[126:129], v[130:133], v[154:157], v[126:129]
	v_mfma_f32_16x16x32_bf16 v[122:125], v[134:137], v[154:157], v[122:125]
	v_mfma_f32_16x16x32_bf16 v[118:121], v[146:149], v[154:157], v[118:121]
	v_mfma_f32_16x16x32_bf16 v[114:117], v[150:153], v[154:157], v[114:117]
	ds_read_b128 v[154:157], v138 offset:4096
	s_waitcnt lgkmcnt(1)
	v_mfma_f32_16x16x32_bf16 v[110:113], v[130:133], v[158:161], v[110:113]
	v_mfma_f32_16x16x32_bf16 v[106:109], v[134:137], v[158:161], v[106:109]
	v_mfma_f32_16x16x32_bf16 v[102:105], v[146:149], v[158:161], v[102:105]
	v_mfma_f32_16x16x32_bf16 v[98:101], v[150:153], v[158:161], v[98:101]
	ds_read_b128 v[158:161], v138 offset:6144
	s_waitcnt lgkmcnt(1)
	v_mfma_f32_16x16x32_bf16 v[94:97], v[130:133], v[154:157], v[94:97]
	v_mfma_f32_16x16x32_bf16 v[90:93], v[134:137], v[154:157], v[90:93]
	v_mfma_f32_16x16x32_bf16 v[86:89], v[146:149], v[154:157], v[86:89]
	v_mfma_f32_16x16x32_bf16 v[82:85], v[150:153], v[154:157], v[82:85]
	ds_read_b128 v[154:157], v138 offset:8192
	s_waitcnt lgkmcnt(1)
	v_mfma_f32_16x16x32_bf16 v[78:81], v[130:133], v[158:161], v[78:81]
	v_mfma_f32_16x16x32_bf16 v[74:77], v[134:137], v[158:161], v[74:77]
	v_mfma_f32_16x16x32_bf16 v[70:73], v[146:149], v[158:161], v[70:73]
	v_mfma_f32_16x16x32_bf16 v[66:69], v[150:153], v[158:161], v[66:69]
	ds_read_b128 v[158:161], v138 offset:10240
	s_waitcnt lgkmcnt(1)
	v_mfma_f32_16x16x32_bf16 v[62:65], v[130:133], v[154:157], v[62:65]
	v_mfma_f32_16x16x32_bf16 v[58:61], v[134:137], v[154:157], v[58:61]
	v_mfma_f32_16x16x32_bf16 v[54:57], v[146:149], v[154:157], v[54:57]
	v_mfma_f32_16x16x32_bf16 v[50:53], v[150:153], v[154:157], v[50:53]
	ds_read_b128 v[154:157], v138 offset:12288
	s_waitcnt lgkmcnt(1)
	v_mfma_f32_16x16x32_bf16 v[46:49], v[130:133], v[158:161], v[46:49]
	v_mfma_f32_16x16x32_bf16 v[42:45], v[134:137], v[158:161], v[42:45]
	v_mfma_f32_16x16x32_bf16 v[38:41], v[146:149], v[158:161], v[38:41]
	v_mfma_f32_16x16x32_bf16 v[34:37], v[150:153], v[158:161], v[34:37]
	ds_read_b128 v[158:161], v138 offset:14336
	s_waitcnt lgkmcnt(1)
;     ...
;   const int row0 = m0 + wm * 32 * MI + r16, cbw = n0 + wn * 64;
;   if constexpr (std::is_invocable_v<EP, int, int, int, const f32x4&, const f32x4&, const f32x4&, const f32x4&>) {
; #pragma unroll
;     for (int a = 0; a < MT; ++a) ep(row0 + 16 * a, cbw, q4, acc[a][0], acc[a][1], acc[a][2], acc[a][3]);
;   } else {
; #pragma unroll
;     for (int a = 0; a < MT; ++a)
; #pragma unroll
;       for (int nt = 0; nt < 4; ++nt)
;         ep(row0 + 16 * a, cbw + 16 * nt + 4 * q4, acc[a][nt][0], acc[a][nt][1], acc[a][nt][2], acc[a][nt][3]);
; DI void phase_resid(char* smem, const Params& p, int layer, const bf16_t* A, int K, const bf16_t* W, int gate_idx, bool first) {
;     ...
;   auto ep = [&](int row, int col, float v0, float v1, float v2, float v3) {
;     const int b = row / TT, t = row - b * TT;
;     const float4 g = *(const float4*)(p.mod + (size_t)(layer * 5 + (t < CTXL ? 4 : b)) * 6144 + gate_idx * 1024 + col);
;     const float4 xo = *(const float4*)(xsrc_row(p, first, row) + col);
;     *(float4*)(xdst_row(p, row) + col) = make_float4(xo.x + g.x * v0, xo.y + g.y * v1, xo.z + g.z * v2, xo.w + g.w * v3);
;   };
	v_mfma_f32_16x16x32_bf16 v[30:33], v[130:133], v[154:157], v[30:33]
	v_mfma_f32_16x16x32_bf16 v[26:29], v[134:137], v[154:157], v[26:29]
	v_mfma_f32_16x16x32_bf16 v[22:25], v[146:149], v[154:157], v[22:25]
	v_mfma_f32_16x16x32_bf16 v[18:21], v[150:153], v[154:157], v[18:21]
	s_waitcnt lgkmcnt(0)
	v_mfma_f32_16x16x32_bf16 v[14:17], v[130:133], v[158:161], v[14:17]
	v_mfma_f32_16x16x32_bf16 v[10:13], v[134:137], v[158:161], v[10:13]
	v_mfma_f32_16x16x32_bf16 v[6:9], v[146:149], v[158:161], v[6:9]
	v_mfma_f32_16x16x32_bf16 v[2:5], v[150:153], v[158:161], v[2:5]
	v_or_b32_e32 v131, s40, v142
	v_lshlrev_b32_e32 v130, 6, v143
	v_lshl_add_u32 v142, v140, 7, v131
	v_lshlrev_b32_e32 v131, 2, v141
	v_or3_b32 v134, v130, v131, s39
	v_mul_hi_i32 v130, v142, s1
	v_lshrrev_b32_e32 v131, 31, v130
	v_ashrrev_i32_e32 v130, 11, v130
	v_add_u32_e32 v130, v130, v131
	v_mad_i32_i24 v131, v130, s90, v142
	s_movk_i32 s39, 0x100
	v_cmp_gt_i32_e32 vcc, s39, v131
	v_add_u32_e32 v132, 0xffffff00, v131
	v_ashrrev_i32_e32 v133, 31, v131
	v_readlane_b32 s40, v254, 1
	v_cndmask_b32_e64 v135, v130, 4, vcc
	v_cndmask_b32_e32 v133, 0, v133, vcc
	v_cndmask_b32_e32 v132, v132, v131, vcc
	v_ashrrev_i32_e32 v131, 31, v130
	v_cndmask_b32_e64 v136, 25, 20, vcc
	v_readlane_b32 s41, v254, 2
	v_lshlrev_b64 v[140:141], v136, v[130:131]
	v_lshlrev_b64 v[150:151], 12, v[132:133]
	v_add_u32_e32 v130, s37, v135
	v_mov_b64_e32 v[132:133], s[40:41]
	s_movk_i32 s40, 0x6000
	v_readlane_b32 s42, v254, 3
	v_readlane_b32 s43, v254, 4
	v_mad_i64_i32 v[130:131], s[16:17], v130, s40, v[132:133]
	s_mov_b64 s[42:43], 0x5000
	v_ashrrev_i32_e32 v135, 31, v134
	v_readlane_b32 s16, v252, 26
	v_lshl_add_u64 v[136:137], v[130:131], 0, s[42:43]
	v_lshlrev_b64 v[130:131], 2, v[134:135]
	v_mov_b32_e32 v135, s16
	v_readlane_b32 s16, v252, 28
	s_waitcnt vmcnt(0)
	s_barrier
	s_nop 0
	v_mov_b32_e32 v143, s16
	v_readlane_b32 s16, v252, 25
	v_cndmask_b32_e32 v139, v135, v143, vcc
	s_nop 0
	v_mov_b32_e32 v144, s16
	v_readlane_b32 s16, v252, 27
	v_readlane_b32 s68, v252, 5
	v_readlane_b32 s80, v252, 17
	v_mov_b32_e32 v145, s16
	v_cndmask_b32_e32 v138, v144, v145, vcc
	global_load_dwordx2 v[138:139], v[138:139], off
	v_readlane_b32 s81, v252, 18
	v_readlane_b32 s82, v252, 19
	v_readlane_b32 s83, v252, 20
	v_mov_b32_e32 v146, s81
	v_mov_b32_e32 v148, s80
	v_mov_b32_e32 v147, s83
	v_mov_b32_e32 v149, s82
	v_cndmask_b32_e32 v155, v146, v147, vcc
	v_cndmask_b32_e32 v154, v148, v149, vcc
	v_lshl_add_u64 v[152:153], v[136:137], 0, v[130:131]
	s_add_i32 s38, s38, s30
	s_cmp_gt_i32 s38, 31
	v_readlane_b32 s44, v254, 5
	v_readlane_b32 s45, v254, 6
	v_readlane_b32 s46, v254, 7
	v_readlane_b32 s47, v254, 8
	v_readlane_b32 s48, v254, 9
	v_readlane_b32 s49, v254, 10
	v_readlane_b32 s50, v254, 11
	v_readlane_b32 s51, v254, 12
	v_readlane_b32 s52, v254, 13
	v_readlane_b32 s53, v254, 14
	v_readlane_b32 s54, v254, 15
	v_readlane_b32 s55, v254, 16
	v_readlane_b32 s69, v252, 6
	v_readlane_b32 s70, v252, 7
	v_readlane_b32 s71, v252, 8
	v_readlane_b32 s72, v252, 9
	v_readlane_b32 s73, v252, 10
	v_readlane_b32 s74, v252, 11
	v_readlane_b32 s75, v252, 12
	v_readlane_b32 s76, v252, 13
	v_readlane_b32 s77, v252, 14
	v_readlane_b32 s78, v252, 15
	v_readlane_b32 s79, v252, 16
	s_waitcnt vmcnt(0)
	v_lshl_add_u64 v[138:139], v[138:139], 0, v[140:141]
	v_lshl_add_u64 v[138:139], v[138:139], 0, v[150:151]
	v_lshl_add_u64 v[140:141], v[154:155], 0, v[140:141]
	v_lshl_add_u64 v[138:139], v[138:139], 0, v[130:131]
	v_lshl_add_u64 v[140:141], v[140:141], 0, v[150:151]
	v_lshl_add_u64 v[140:141], v[140:141], 0, v[130:131]
	s_cselect_b64 s[16:17], -1, 0
	global_load_dwordx4 v[156:159], v[152:153], off
	global_load_dwordx4 v[160:163], v[152:153], off offset:64
	global_load_dwordx4 v[164:167], v[152:153], off offset:128
	global_load_dwordx4 v[168:171], v[152:153], off offset:192
	global_load_dwordx4 v[172:175], v[138:139], off
	global_load_dwordx4 v[176:179], v[138:139], off offset:64
	global_load_dwordx4 v[180:183], v[138:139], off offset:128
	global_load_dwordx4 v[184:187], v[138:139], off offset:192
	v_add_co_u32_e32 v138, vcc, 0x10000, v138
	s_nop 1
	v_addc_co_u32_e32 v139, vcc, 0, v139, vcc
	global_load_dwordx4 v[198:201], v[138:139], off
	global_load_dwordx4 v[202:205], v[138:139], off offset:64
	global_load_dwordx4 v[206:209], v[138:139], off offset:128
	global_load_dwordx4 v[210:213], v[138:139], off offset:192
	v_add_co_u32_e32 v138, vcc, 0x10000, v138
	s_nop 1
	v_addc_co_u32_e32 v139, vcc, 0, v139, vcc
	global_load_dwordx4 v[214:217], v[138:139], off
	global_load_dwordx4 v[218:221], v[138:139], off offset:64
	global_load_dwordx4 v[222:225], v[138:139], off offset:128
	global_load_dwordx4 v[142:145], v[138:139], off offset:192
	v_add_co_u32_e32 v138, vcc, 0x10000, v138
	s_nop 1
	v_addc_co_u32_e32 v139, vcc, 0, v139, vcc
	s_waitcnt vmcnt(8)
	v_pk_fma_f32 v[126:127], v[126:127], v[156:157], v[172:173]
	v_pk_fma_f32 v[128:129], v[128:129], v[158:159], v[174:175]
	v_pk_fma_f32 v[122:123], v[122:123], v[160:161], v[176:177]
	v_pk_fma_f32 v[124:125], v[124:125], v[162:163], v[178:179]
	v_pk_fma_f32 v[118:119], v[118:119], v[164:165], v[180:181]
	v_pk_fma_f32 v[120:121], v[120:121], v[166:167], v[182:183]
	v_pk_fma_f32 v[114:115], v[114:115], v[168:169], v[184:185]
	v_pk_fma_f32 v[116:117], v[116:117], v[170:171], v[186:187]
	global_store_dwordx4 v[140:141], v[126:129], off
	global_store_dwordx4 v[140:141], v[122:125], off offset:64
	global_store_dwordx4 v[140:141], v[118:121], off offset:128
	global_store_dwordx4 v[140:141], v[114:117], off offset:192
	v_add_co_u32_e32 v140, vcc, 0x10000, v140
	s_nop 1
	v_addc_co_u32_e32 v141, vcc, 0, v141, vcc
	global_load_dwordx4 v[172:175], v[138:139], off
	global_load_dwordx4 v[176:179], v[138:139], off offset:64
	global_load_dwordx4 v[180:183], v[138:139], off offset:128
	global_load_dwordx4 v[184:187], v[138:139], off offset:192
	v_add_co_u32_e32 v138, vcc, 0x10000, v138
	s_nop 1
	v_addc_co_u32_e32 v139, vcc, 0, v139, vcc
	s_waitcnt vmcnt(12)
;     ...
; #pragma unroll
;     for (int a = 0; a < MT; ++a)
; #pragma unroll
;       for (int nt = 0; nt < 4; ++nt)
;         ep(row0 + 16 * a, cbw + 16 * nt + 4 * q4, acc[a][nt][0], acc[a][nt][1], acc[a][nt][2], acc[a][nt][3]);
; DI void phase_resid(char* smem, const Params& p, int layer, const bf16_t* A, int K, const bf16_t* W, int gate_idx, bool first) {
;     ...
;   auto ep = [&](int row, int col, float v0, float v1, float v2, float v3) {
;     const int b = row / TT, t = row - b * TT;
;     const float4 g = *(const float4*)(p.mod + (size_t)(layer * 5 + (t < CTXL ? 4 : b)) * 6144 + gate_idx * 1024 + col);
;     const float4 xo = *(const float4*)(xsrc_row(p, first, row) + col);
;     *(float4*)(xdst_row(p, row) + col) = make_float4(xo.x + g.x * v0, xo.y + g.y * v1, xo.z + g.z * v2, xo.w + g.w * v3);
;   };
	v_pk_fma_f32 v[110:111], v[110:111], v[156:157], v[198:199]
	v_pk_fma_f32 v[112:113], v[112:113], v[158:159], v[200:201]
	v_pk_fma_f32 v[106:107], v[106:107], v[160:161], v[202:203]
	v_pk_fma_f32 v[108:109], v[108:109], v[162:163], v[204:205]
	v_pk_fma_f32 v[102:103], v[102:103], v[164:165], v[206:207]
	v_pk_fma_f32 v[104:105], v[104:105], v[166:167], v[208:209]
	v_pk_fma_f32 v[98:99], v[98:99], v[168:169], v[210:211]
	v_pk_fma_f32 v[100:101], v[100:101], v[170:171], v[212:213]
	global_store_dwordx4 v[140:141], v[110:113], off
	global_store_dwordx4 v[140:141], v[106:109], off offset:64
	global_store_dwordx4 v[140:141], v[102:105], off offset:128
	global_store_dwordx4 v[140:141], v[98:101], off offset:192
	v_add_co_u32_e32 v140, vcc, 0x10000, v140
	s_nop 1
	v_addc_co_u32_e32 v141, vcc, 0, v141, vcc
	global_load_dwordx4 v[198:201], v[138:139], off
	global_load_dwordx4 v[202:205], v[138:139], off offset:64
	global_load_dwordx4 v[206:209], v[138:139], off offset:128
	global_load_dwordx4 v[210:213], v[138:139], off offset:192
	v_add_co_u32_e32 v138, vcc, 0x10000, v138
	s_nop 1
	v_addc_co_u32_e32 v139, vcc, 0, v139, vcc
	s_waitcnt vmcnt(16)
	v_pk_fma_f32 v[94:95], v[94:95], v[156:157], v[214:215]
	v_pk_fma_f32 v[96:97], v[96:97], v[158:159], v[216:217]
	v_pk_fma_f32 v[90:91], v[90:91], v[160:161], v[218:219]
	v_pk_fma_f32 v[92:93], v[92:93], v[162:163], v[220:221]
	v_pk_fma_f32 v[86:87], v[86:87], v[164:165], v[222:223]
	v_pk_fma_f32 v[88:89], v[88:89], v[166:167], v[224:225]
	v_pk_fma_f32 v[82:83], v[82:83], v[168:169], v[142:143]
	v_pk_fma_f32 v[84:85], v[84:85], v[170:171], v[144:145]
	global_store_dwordx4 v[140:141], v[94:97], off
	global_store_dwordx4 v[140:141], v[90:93], off offset:64
	global_store_dwordx4 v[140:141], v[86:89], off offset:128
	global_store_dwordx4 v[140:141], v[82:85], off offset:192
	v_add_co_u32_e32 v140, vcc, 0x10000, v140
	s_nop 1
	v_addc_co_u32_e32 v141, vcc, 0, v141, vcc
	global_load_dwordx4 v[214:217], v[138:139], off
	global_load_dwordx4 v[218:221], v[138:139], off offset:64
	global_load_dwordx4 v[222:225], v[138:139], off offset:128
	global_load_dwordx4 v[142:145], v[138:139], off offset:192
	v_add_co_u32_e32 v138, vcc, 0x10000, v138
	s_nop 1
	v_addc_co_u32_e32 v139, vcc, 0, v139, vcc
	s_waitcnt vmcnt(16)
	v_pk_fma_f32 v[78:79], v[78:79], v[156:157], v[172:173]
	v_pk_fma_f32 v[80:81], v[80:81], v[158:159], v[174:175]
	v_pk_fma_f32 v[74:75], v[74:75], v[160:161], v[176:177]
	v_pk_fma_f32 v[76:77], v[76:77], v[162:163], v[178:179]
	v_pk_fma_f32 v[70:71], v[70:71], v[164:165], v[180:181]
	v_pk_fma_f32 v[72:73], v[72:73], v[166:167], v[182:183]
	v_pk_fma_f32 v[66:67], v[66:67], v[168:169], v[184:185]
	v_pk_fma_f32 v[68:69], v[68:69], v[170:171], v[186:187]
	global_store_dwordx4 v[140:141], v[78:81], off
	global_store_dwordx4 v[140:141], v[74:77], off offset:64
	global_store_dwordx4 v[140:141], v[70:73], off offset:128
	global_store_dwordx4 v[140:141], v[66:69], off offset:192
	v_add_co_u32_e32 v140, vcc, 0x10000, v140
	s_nop 1
	v_addc_co_u32_e32 v141, vcc, 0, v141, vcc
	global_load_dwordx4 v[172:175], v[138:139], off
	global_load_dwordx4 v[176:179], v[138:139], off offset:64
	global_load_dwordx4 v[180:183], v[138:139], off offset:128
	global_load_dwordx4 v[184:187], v[138:139], off offset:192
	v_add_co_u32_e32 v138, vcc, 0x10000, v138
	s_nop 1
	v_addc_co_u32_e32 v139, vcc, 0, v139, vcc
	s_waitcnt vmcnt(16)
	v_pk_fma_f32 v[62:63], v[62:63], v[156:157], v[198:199]
	v_pk_fma_f32 v[64:65], v[64:65], v[158:159], v[200:201]
	v_pk_fma_f32 v[58:59], v[58:59], v[160:161], v[202:203]
	v_pk_fma_f32 v[60:61], v[60:61], v[162:163], v[204:205]
	v_pk_fma_f32 v[54:55], v[54:55], v[164:165], v[206:207]
	v_pk_fma_f32 v[56:57], v[56:57], v[166:167], v[208:209]
	v_pk_fma_f32 v[50:51], v[50:51], v[168:169], v[210:211]
	v_pk_fma_f32 v[52:53], v[52:53], v[170:171], v[212:213]
	global_store_dwordx4 v[140:141], v[62:65], off
	global_store_dwordx4 v[140:141], v[58:61], off offset:64
	global_store_dwordx4 v[140:141], v[54:57], off offset:128
	global_store_dwordx4 v[140:141], v[50:53], off offset:192
	v_add_co_u32_e32 v140, vcc, 0x10000, v140
	s_nop 1
	v_addc_co_u32_e32 v141, vcc, 0, v141, vcc
	global_load_dwordx4 v[198:201], v[138:139], off
	global_load_dwordx4 v[202:205], v[138:139], off offset:64
	global_load_dwordx4 v[206:209], v[138:139], off offset:128
	global_load_dwordx4 v[210:213], v[138:139], off offset:192
	s_waitcnt vmcnt(16)
	v_pk_fma_f32 v[46:47], v[46:47], v[156:157], v[214:215]
	v_pk_fma_f32 v[48:49], v[48:49], v[158:159], v[216:217]
	v_pk_fma_f32 v[42:43], v[42:43], v[160:161], v[218:219]
	v_pk_fma_f32 v[44:45], v[44:45], v[162:163], v[220:221]
	v_pk_fma_f32 v[38:39], v[38:39], v[164:165], v[222:223]
	v_pk_fma_f32 v[40:41], v[40:41], v[166:167], v[224:225]
	v_pk_fma_f32 v[34:35], v[34:35], v[168:169], v[142:143]
	v_pk_fma_f32 v[36:37], v[36:37], v[170:171], v[144:145]
	global_store_dwordx4 v[140:141], v[46:49], off
	global_store_dwordx4 v[140:141], v[42:45], off offset:64
	global_store_dwordx4 v[140:141], v[38:41], off offset:128
	global_store_dwordx4 v[140:141], v[34:37], off offset:192
	v_add_co_u32_e32 v140, vcc, 0x10000, v140
	s_nop 1
	v_addc_co_u32_e32 v141, vcc, 0, v141, vcc
	s_waitcnt vmcnt(12)
	v_pk_fma_f32 v[30:31], v[30:31], v[156:157], v[172:173]
	v_pk_fma_f32 v[32:33], v[32:33], v[158:159], v[174:175]
	v_pk_fma_f32 v[26:27], v[26:27], v[160:161], v[176:177]
	v_pk_fma_f32 v[28:29], v[28:29], v[162:163], v[178:179]
	v_pk_fma_f32 v[22:23], v[22:23], v[164:165], v[180:181]
	v_pk_fma_f32 v[24:25], v[24:25], v[166:167], v[182:183]
	v_pk_fma_f32 v[18:19], v[18:19], v[168:169], v[184:185]
	v_pk_fma_f32 v[20:21], v[20:21], v[170:171], v[186:187]
	global_store_dwordx4 v[140:141], v[30:33], off
	global_store_dwordx4 v[140:141], v[26:29], off offset:64
	global_store_dwordx4 v[140:141], v[22:25], off offset:128
	global_store_dwordx4 v[140:141], v[18:21], off offset:192
	v_add_co_u32_e32 v140, vcc, 0x10000, v140
	s_nop 1
	v_addc_co_u32_e32 v141, vcc, 0, v141, vcc
	s_waitcnt vmcnt(8)
	v_pk_fma_f32 v[14:15], v[14:15], v[156:157], v[198:199]
	v_pk_fma_f32 v[16:17], v[16:17], v[158:159], v[200:201]
	v_pk_fma_f32 v[10:11], v[10:11], v[160:161], v[202:203]
	v_pk_fma_f32 v[12:13], v[12:13], v[162:163], v[204:205]
	v_pk_fma_f32 v[6:7], v[6:7], v[164:165], v[206:207]
	v_pk_fma_f32 v[8:9], v[8:9], v[166:167], v[208:209]
	v_pk_fma_f32 v[2:3], v[2:3], v[168:169], v[210:211]
	v_pk_fma_f32 v[4:5], v[4:5], v[170:171], v[212:213]
	global_store_dwordx4 v[140:141], v[14:17], off
	global_store_dwordx4 v[140:141], v[10:13], off offset:64
	global_store_dwordx4 v[140:141], v[6:9], off offset:128
	global_store_dwordx4 v[140:141], v[2:5], off offset:192
	s_branch .LBB0_41

; #define MFMA16(a, b, c) __builtin_amdgcn_mfma_f32_16x16x32_bf16((a), (b), (c), 0, 0, 0)
;     ...
;   for (int kt = 0; kt < nk; ++kt) {
;     const int buf = kt & 1;
;     const char* cA = smem + buf * STAGE + (wm * 32 * MI + r16) * 128;
;     const char* cB = smem + buf * STAGE + 32768 + (wn * 64 + r16) * 128;
; #pragma unroll
;     for (int k2 = 0; k2 < 2; ++k2) {
;       if (k2 == 1 && kt + 1 < nk) STAGE_TILE(buf ^ 1, (kt + 1) * 64)
;       const int po = ((4 * k2 + q4) ^ swz) * 16;
;       bf16x8 bf[4];
; #pragma unroll
;       for (int nt = 0; nt < 4; ++nt) bf[nt] = *(const bf16x8*)(cB + nt * 16 * 128 + po);
;       bf16x8 afc = *(const bf16x8*)(cA + po);
; #pragma unroll
;       for (int a = 0; a < MT; ++a) {
;         bf16x8 afn = afc;
;         if (a + 1 < MT) afn = *(const bf16x8*)(cA + (a + 1) * 16 * 128 + po);
;         __builtin_amdgcn_sched_barrier(0);
; #pragma unroll
;         for (int nt = 0; nt < 4; ++nt) acc[a][nt] = MFMA16(bf[nt], afc, acc[a][nt]);
;         __builtin_amdgcn_sched_barrier(0);
;         afc = afn;
;       }
;     }
;     asm volatile("s_waitcnt vmcnt(0)" ::: "memory");
;     __syncthreads();
;   }
.LBB0_75:
	s_and_b32 s41, s40, 0x10000
	s_add_i32 s42, s41, 0
	v_add_u32_e32 v190, s42, v147
	v_add_u32_e32 v162, v190, v146
	v_add_u32_e32 v149, s42, v148
	v_add_u32_e32 v202, v149, v146
	s_xor_b32 s41, s41, 0x10000
	ds_read_b128 v[150:153], v162 offset:32768
	ds_read_b128 v[166:169], v202
	ds_read_b128 v[154:157], v162 offset:34816
	ds_read_b128 v[158:161], v162 offset:36864
	ds_read_b128 v[162:165], v162 offset:38912
	ds_read_b128 v[170:173], v202 offset:2048
	s_waitcnt lgkmcnt(4)
	v_mfma_f32_16x16x32_bf16 v[126:129], v[150:153], v[166:169], v[126:129]
	v_readfirstlane_b32 s42, v145
	s_waitcnt lgkmcnt(3)
	v_mfma_f32_16x16x32_bf16 v[122:125], v[154:157], v[166:169], v[122:125]
	s_nop 0
	s_waitcnt lgkmcnt(2)
	v_mfma_f32_16x16x32_bf16 v[118:121], v[158:161], v[166:169], v[118:121]
	s_add_u32 s42, s42, s41
	s_waitcnt lgkmcnt(1)
	v_mfma_f32_16x16x32_bf16 v[114:117], v[162:165], v[166:169], v[114:117]
	ds_read_b128 v[166:169], v202 offset:4096
	s_add_u32 m0, s42, 0x0
	s_waitcnt lgkmcnt(1)
	v_mfma_f32_16x16x32_bf16 v[110:113], v[150:153], v[170:173], v[110:113]
	global_load_lds_dwordx4 v174, s[100:101]
	v_mfma_f32_16x16x32_bf16 v[106:109], v[154:157], v[170:173], v[106:109]
	s_add_u32 m0, s42, 0x2000
	v_mfma_f32_16x16x32_bf16 v[102:105], v[158:161], v[170:173], v[102:105]
	global_load_lds_dwordx4 v175, s[100:101]
	v_mfma_f32_16x16x32_bf16 v[98:101], v[162:165], v[170:173], v[98:101]
	ds_read_b128 v[170:173], v202 offset:6144
	s_add_u32 m0, s42, 0x4000
	s_waitcnt lgkmcnt(1)
	v_mfma_f32_16x16x32_bf16 v[94:97], v[150:153], v[166:169], v[94:97]
	global_load_lds_dwordx4 v176, s[100:101]
	v_mfma_f32_16x16x32_bf16 v[90:93], v[154:157], v[166:169], v[90:93]
	s_add_u32 m0, s42, 0x6000
	v_mfma_f32_16x16x32_bf16 v[86:89], v[158:161], v[166:169], v[86:89]
	global_load_lds_dwordx4 v177, s[100:101]
	v_mfma_f32_16x16x32_bf16 v[82:85], v[162:165], v[166:169], v[82:85]
	ds_read_b128 v[166:169], v202 offset:8192
	s_add_u32 m0, s42, 0x8000
	s_waitcnt lgkmcnt(1)
	v_mfma_f32_16x16x32_bf16 v[78:81], v[150:153], v[170:173], v[78:81]
	global_load_lds_dwordx4 v178, s[100:101]
	v_mfma_f32_16x16x32_bf16 v[74:77], v[154:157], v[170:173], v[74:77]
	s_add_u32 m0, s42, 0xa000
	v_mfma_f32_16x16x32_bf16 v[70:73], v[158:161], v[170:173], v[70:73]
	global_load_lds_dwordx4 v179, s[100:101]
	v_mfma_f32_16x16x32_bf16 v[66:69], v[162:165], v[170:173], v[66:69]
	ds_read_b128 v[170:173], v202 offset:10240
	s_add_u32 m0, s42, 0xc000
	s_waitcnt lgkmcnt(1)
	v_mfma_f32_16x16x32_bf16 v[62:65], v[150:153], v[166:169], v[62:65]
	global_load_lds_dwordx4 v180, s[100:101]
	v_mfma_f32_16x16x32_bf16 v[58:61], v[154:157], v[166:169], v[58:61]
	s_add_u32 m0, s42, 0xe000
	v_mfma_f32_16x16x32_bf16 v[54:57], v[158:161], v[166:169], v[54:57]
	global_load_lds_dwordx4 v181, s[100:101]
	v_mfma_f32_16x16x32_bf16 v[50:53], v[162:165], v[166:169], v[50:53]
	ds_read_b128 v[166:169], v202 offset:12288
	v_add_u32_e32 v203, v190, v144
	s_waitcnt lgkmcnt(1)
	v_mfma_f32_16x16x32_bf16 v[46:49], v[150:153], v[170:173], v[46:49]
	v_add_u32_e32 v192, v149, v144
	v_mfma_f32_16x16x32_bf16 v[42:45], v[154:157], v[170:173], v[42:45]
	ds_read_b128 v[204:207], v203 offset:32768
	v_mfma_f32_16x16x32_bf16 v[38:41], v[158:161], v[170:173], v[38:41]
	ds_read_b128 v[208:211], v203 offset:34816
	v_mfma_f32_16x16x32_bf16 v[34:37], v[162:165], v[170:173], v[34:37]
	ds_read_b128 v[170:173], v202 offset:14336
	ds_read_b128 v[212:215], v203 offset:36864
	s_waitcnt lgkmcnt(4)
	v_mfma_f32_16x16x32_bf16 v[30:33], v[150:153], v[166:169], v[30:33]
	ds_read_b128 v[216:219], v203 offset:38912
	v_mfma_f32_16x16x32_bf16 v[26:29], v[154:157], v[166:169], v[26:29]
	ds_read_b128 v[220:223], v192
	v_mfma_f32_16x16x32_bf16 v[22:25], v[158:161], v[166:169], v[22:25]
	ds_read_b128 v[198:201], v192 offset:2048
	v_mfma_f32_16x16x32_bf16 v[18:21], v[162:165], v[166:169], v[18:21]
	s_waitcnt lgkmcnt(4)
	v_mfma_f32_16x16x32_bf16 v[14:17], v[150:153], v[170:173], v[14:17]
	v_mfma_f32_16x16x32_bf16 v[10:13], v[154:157], v[170:173], v[10:13]
	v_mfma_f32_16x16x32_bf16 v[6:9], v[158:161], v[170:173], v[6:9]
	v_mfma_f32_16x16x32_bf16 v[2:5], v[162:165], v[170:173], v[2:5]
	s_waitcnt lgkmcnt(1)
	v_mfma_f32_16x16x32_bf16 v[126:129], v[204:207], v[220:223], v[126:129]
	s_add_u32 s100, s100, 0x80
	v_mfma_f32_16x16x32_bf16 v[122:125], v[208:211], v[220:223], v[122:125]
	s_addc_u32 s101, s101, 0
	v_mfma_f32_16x16x32_bf16 v[118:121], v[212:215], v[220:223], v[118:121]
	s_add_u32 s16, s16, 0x80
	v_mfma_f32_16x16x32_bf16 v[114:117], v[216:219], v[220:223], v[114:117]
	ds_read_b128 v[220:223], v192 offset:4096
	s_waitcnt lgkmcnt(1)
	v_mfma_f32_16x16x32_bf16 v[110:113], v[204:207], v[198:201], v[110:113]
	s_addc_u32 s17, s17, 0
	v_mfma_f32_16x16x32_bf16 v[106:109], v[208:211], v[198:201], v[106:109]
	s_add_i32 s40, s40, 0x10000
	v_mfma_f32_16x16x32_bf16 v[102:105], v[212:215], v[198:201], v[102:105]
	v_mfma_f32_16x16x32_bf16 v[98:101], v[216:219], v[198:201], v[98:101]
	ds_read_b128 v[198:201], v192 offset:6144
	s_waitcnt lgkmcnt(1)
	v_mfma_f32_16x16x32_bf16 v[94:97], v[204:207], v[220:223], v[94:97]
	v_mfma_f32_16x16x32_bf16 v[90:93], v[208:211], v[220:223], v[90:93]
	v_mfma_f32_16x16x32_bf16 v[86:89], v[212:215], v[220:223], v[86:89]
	v_mfma_f32_16x16x32_bf16 v[82:85], v[216:219], v[220:223], v[82:85]
	ds_read_b128 v[220:223], v192 offset:8192
	s_waitcnt lgkmcnt(1)
	v_mfma_f32_16x16x32_bf16 v[78:81], v[204:207], v[198:201], v[78:81]
	v_mfma_f32_16x16x32_bf16 v[74:77], v[208:211], v[198:201], v[74:77]
	v_mfma_f32_16x16x32_bf16 v[70:73], v[212:215], v[198:201], v[70:73]
	v_mfma_f32_16x16x32_bf16 v[66:69], v[216:219], v[198:201], v[66:69]
	ds_read_b128 v[198:201], v192 offset:10240
	s_waitcnt lgkmcnt(1)
	v_mfma_f32_16x16x32_bf16 v[62:65], v[204:207], v[220:223], v[62:65]
	v_mfma_f32_16x16x32_bf16 v[58:61], v[208:211], v[220:223], v[58:61]
	v_mfma_f32_16x16x32_bf16 v[54:57], v[212:215], v[220:223], v[54:57]
	v_mfma_f32_16x16x32_bf16 v[50:53], v[216:219], v[220:223], v[50:53]
	ds_read_b128 v[220:223], v192 offset:12288
	s_waitcnt lgkmcnt(1)
	v_mfma_f32_16x16x32_bf16 v[46:49], v[204:207], v[198:201], v[46:49]
	v_mfma_f32_16x16x32_bf16 v[42:45], v[208:211], v[198:201], v[42:45]
	v_mfma_f32_16x16x32_bf16 v[38:41], v[212:215], v[198:201], v[38:41]
	v_mfma_f32_16x16x32_bf16 v[34:37], v[216:219], v[198:201], v[34:37]
	ds_read_b128 v[198:201], v192 offset:14336
	s_waitcnt lgkmcnt(1)
	v_mfma_f32_16x16x32_bf16 v[30:33], v[204:207], v[220:223], v[30:33]
	v_mfma_f32_16x16x32_bf16 v[26:29], v[208:211], v[220:223], v[26:29]
	v_mfma_f32_16x16x32_bf16 v[22:25], v[212:215], v[220:223], v[22:25]
	v_mfma_f32_16x16x32_bf16 v[18:21], v[216:219], v[220:223], v[18:21]
	s_waitcnt lgkmcnt(0)
	v_mfma_f32_16x16x32_bf16 v[14:17], v[204:207], v[198:201], v[14:17]
	v_mfma_f32_16x16x32_bf16 v[10:13], v[208:211], v[198:201], v[10:13]
	v_mfma_f32_16x16x32_bf16 v[6:9], v[212:215], v[198:201], v[6:9]
	v_mfma_f32_16x16x32_bf16 v[2:5], v[216:219], v[198:201], v[2:5]
	s_cmpk_lg_i32 s16, 0x780
	s_waitcnt vmcnt(0)
	s_barrier
; #define MFMA16(a, b, c) __builtin_amdgcn_mfma_f32_16x16x32_bf16((a), (b), (c), 0, 0, 0)
;     ...
;   for (int kt = 0; kt < nk; ++kt) {
;     const int buf = kt & 1;
;     const char* cA = smem + buf * STAGE + (wm * 32 * MI + r16) * 128;
;     const char* cB = smem + buf * STAGE + 32768 + (wn * 64 + r16) * 128;
; #pragma unroll
;     for (int k2 = 0; k2 < 2; ++k2) {
;       if (k2 == 1 && kt + 1 < nk) STAGE_TILE(buf ^ 1, (kt + 1) * 64)
;       const int po = ((4 * k2 + q4) ^ swz) * 16;
;       bf16x8 bf[4];
; #pragma unroll
;       for (int nt = 0; nt < 4; ++nt) bf[nt] = *(const bf16x8*)(cB + nt * 16 * 128 + po);
;       bf16x8 afc = *(const bf16x8*)(cA + po);
; #pragma unroll
;       for (int a = 0; a < MT; ++a) {
;         bf16x8 afn = afc;
;         if (a + 1 < MT) afn = *(const bf16x8*)(cA + (a + 1) * 16 * 128 + po);
;         __builtin_amdgcn_sched_barrier(0);
; #pragma unroll
;         for (int nt = 0; nt < 4; ++nt) acc[a][nt] = MFMA16(bf[nt], afc, acc[a][nt]);
;         __builtin_amdgcn_sched_barrier(0);
;         afc = afn;
;       }
;     }
;     asm volatile("s_waitcnt vmcnt(0)" ::: "memory");
;     __syncthreads();
;   }
	s_cbranch_scc1 .LBB0_75
	s_add_i32 s16, 0, 0x10000
	v_add_u32_e32 v138, s16, v148
	v_readlane_b32 s16, v254, 18
	s_nop 1
	v_add_u32_e32 v139, s16, v147
	v_add_u32_e32 v145, v139, v146
	ds_read_b128 v[130:133], v145
	ds_read_b128 v[134:137], v145 offset:2048
	ds_read_b128 v[148:151], v145 offset:4096
	ds_read_b128 v[152:155], v145 offset:6144
	v_add_u32_e32 v145, v138, v146
	ds_read_b128 v[156:159], v145
	ds_read_b128 v[160:163], v145 offset:2048
	s_waitcnt lgkmcnt(1)
	v_mfma_f32_16x16x32_bf16 v[126:129], v[130:133], v[156:159], v[126:129]
	v_mfma_f32_16x16x32_bf16 v[122:125], v[134:137], v[156:159], v[122:125]
	v_mfma_f32_16x16x32_bf16 v[118:121], v[148:151], v[156:159], v[118:121]
	v_mfma_f32_16x16x32_bf16 v[114:117], v[152:155], v[156:159], v[114:117]
	ds_read_b128 v[156:159], v145 offset:4096
	s_waitcnt lgkmcnt(1)
	v_mfma_f32_16x16x32_bf16 v[110:113], v[130:133], v[160:163], v[110:113]
	v_mfma_f32_16x16x32_bf16 v[106:109], v[134:137], v[160:163], v[106:109]
	v_mfma_f32_16x16x32_bf16 v[102:105], v[148:151], v[160:163], v[102:105]
	v_mfma_f32_16x16x32_bf16 v[98:101], v[152:155], v[160:163], v[98:101]
	ds_read_b128 v[160:163], v145 offset:6144
	s_waitcnt lgkmcnt(1)
	v_mfma_f32_16x16x32_bf16 v[94:97], v[130:133], v[156:159], v[94:97]
	v_mfma_f32_16x16x32_bf16 v[90:93], v[134:137], v[156:159], v[90:93]
	v_mfma_f32_16x16x32_bf16 v[86:89], v[148:151], v[156:159], v[86:89]
	v_mfma_f32_16x16x32_bf16 v[82:85], v[152:155], v[156:159], v[82:85]
	ds_read_b128 v[156:159], v145 offset:8192
	s_waitcnt lgkmcnt(1)
	v_mfma_f32_16x16x32_bf16 v[78:81], v[130:133], v[160:163], v[78:81]
	v_mfma_f32_16x16x32_bf16 v[74:77], v[134:137], v[160:163], v[74:77]
	v_mfma_f32_16x16x32_bf16 v[70:73], v[148:151], v[160:163], v[70:73]
	v_mfma_f32_16x16x32_bf16 v[66:69], v[152:155], v[160:163], v[66:69]
	ds_read_b128 v[160:163], v145 offset:10240
	s_waitcnt lgkmcnt(1)
	v_mfma_f32_16x16x32_bf16 v[62:65], v[130:133], v[156:159], v[62:65]
	v_mfma_f32_16x16x32_bf16 v[58:61], v[134:137], v[156:159], v[58:61]
	v_mfma_f32_16x16x32_bf16 v[54:57], v[148:151], v[156:159], v[54:57]
	v_mfma_f32_16x16x32_bf16 v[50:53], v[152:155], v[156:159], v[50:53]
	ds_read_b128 v[156:159], v145 offset:12288
	s_waitcnt lgkmcnt(1)
	v_mfma_f32_16x16x32_bf16 v[46:49], v[130:133], v[160:163], v[46:49]
	v_mfma_f32_16x16x32_bf16 v[42:45], v[134:137], v[160:163], v[42:45]
	v_mfma_f32_16x16x32_bf16 v[38:41], v[148:151], v[160:163], v[38:41]
	v_mfma_f32_16x16x32_bf16 v[34:37], v[152:155], v[160:163], v[34:37]
	ds_read_b128 v[160:163], v145 offset:14336
	s_waitcnt lgkmcnt(1)
	v_mfma_f32_16x16x32_bf16 v[30:33], v[130:133], v[156:159], v[30:33]
	v_mfma_f32_16x16x32_bf16 v[26:29], v[134:137], v[156:159], v[26:29]
	v_mfma_f32_16x16x32_bf16 v[22:25], v[148:151], v[156:159], v[22:25]
	v_mfma_f32_16x16x32_bf16 v[18:21], v[152:155], v[156:159], v[18:21]
	s_waitcnt lgkmcnt(0)
	v_mfma_f32_16x16x32_bf16 v[14:17], v[130:133], v[160:163], v[14:17]
	v_mfma_f32_16x16x32_bf16 v[10:13], v[134:137], v[160:163], v[10:13]
	v_mfma_f32_16x16x32_bf16 v[6:9], v[148:151], v[160:163], v[6:9]
	v_mfma_f32_16x16x32_bf16 v[2:5], v[152:155], v[160:163], v[2:5]
	v_add_u32_e32 v139, v139, v144
	ds_read_b128 v[130:133], v139
	ds_read_b128 v[134:137], v139 offset:2048
	ds_read_b128 v[146:149], v139 offset:4096
	ds_read_b128 v[150:153], v139 offset:6144
	v_add_u32_e32 v138, v138, v144
	ds_read_b128 v[154:157], v138
	ds_read_b128 v[158:161], v138 offset:2048
	s_waitcnt lgkmcnt(1)
	v_mfma_f32_16x16x32_bf16 v[126:129], v[130:133], v[154:157], v[126:129]
	v_mfma_f32_16x16x32_bf16 v[122:125], v[134:137], v[154:157], v[122:125]
	v_mfma_f32_16x16x32_bf16 v[118:121], v[146:149], v[154:157], v[118:121]
	v_mfma_f32_16x16x32_bf16 v[114:117], v[150:153], v[154:157], v[114:117]
	ds_read_b128 v[154:157], v138 offset:4096
	s_waitcnt lgkmcnt(1)
	v_mfma_f32_16x16x32_bf16 v[162:165], v[130:133], v[158:161], v[110:113]
	v_mfma_f32_16x16x32_bf16 v[166:169], v[134:137], v[158:161], v[106:109]
	v_mfma_f32_16x16x32_bf16 v[102:105], v[146:149], v[158:161], v[102:105]
	v_mfma_f32_16x16x32_bf16 v[98:101], v[150:153], v[158:161], v[98:101]
	s_nop 0
	ds_read_b128 v[106:109], v138 offset:6144
	s_waitcnt lgkmcnt(1)
	v_mfma_f32_16x16x32_bf16 v[94:97], v[130:133], v[154:157], v[94:97]
	v_mfma_f32_16x16x32_bf16 v[90:93], v[134:137], v[154:157], v[90:93]
	v_mfma_f32_16x16x32_bf16 v[86:89], v[146:149], v[154:157], v[86:89]
	v_mfma_f32_16x16x32_bf16 v[82:85], v[150:153], v[154:157], v[82:85]
	ds_read_b128 v[110:113], v138 offset:8192
	s_waitcnt lgkmcnt(1)
	v_mfma_f32_16x16x32_bf16 v[78:81], v[130:133], v[106:109], v[78:81]
	v_mfma_f32_16x16x32_bf16 v[74:77], v[134:137], v[106:109], v[74:77]
	v_mfma_f32_16x16x32_bf16 v[70:73], v[146:149], v[106:109], v[70:73]
	v_mfma_f32_16x16x32_bf16 v[66:69], v[150:153], v[106:109], v[66:69]
	ds_read_b128 v[106:109], v138 offset:10240
	s_waitcnt lgkmcnt(1)
	v_mfma_f32_16x16x32_bf16 v[62:65], v[130:133], v[110:113], v[62:65]
	v_mfma_f32_16x16x32_bf16 v[58:61], v[134:137], v[110:113], v[58:61]
	v_mfma_f32_16x16x32_bf16 v[54:57], v[146:149], v[110:113], v[54:57]
	v_mfma_f32_16x16x32_bf16 v[50:53], v[150:153], v[110:113], v[50:53]
	ds_read_b128 v[110:113], v138 offset:12288
	s_waitcnt lgkmcnt(1)
	v_mfma_f32_16x16x32_bf16 v[46:49], v[130:133], v[106:109], v[46:49]
	v_mfma_f32_16x16x32_bf16 v[42:45], v[134:137], v[106:109], v[42:45]
	v_mfma_f32_16x16x32_bf16 v[38:41], v[146:149], v[106:109], v[38:41]
	v_mfma_f32_16x16x32_bf16 v[34:37], v[150:153], v[106:109], v[34:37]
	ds_read_b128 v[106:109], v138 offset:14336
	s_waitcnt lgkmcnt(1)
; DI unsigned pack2(float a, float b) { hwf2_t f = {a, b}; return __builtin_bit_cast(unsigned, __builtin_convertvector(f, hwbf2_t)); }
; DI float fsigmoid(float x) { return __builtin_amdgcn_rcpf(1.f + __expf(-x)); }
; DI void phase_ffn_up(char* smem, const Params& p, int layer) {
;     ...
;   auto ep = [=](int row, int cb, int q4, const f32x4& c0, const f32x4& c1, const f32x4& c2, const f32x4& c3) {
;     const uint4 o = make_uint4(pack2(c0[0] * fsigmoid(c0[0]) * c0[1], c0[2] * fsigmoid(c0[2]) * c0[3]),
;                                pack2(c1[0] * fsigmoid(c1[0]) * c1[1], c1[2] * fsigmoid(c1[2]) * c1[3]),
;                                pack2(c2[0] * fsigmoid(c2[0]) * c2[1], c2[2] * fsigmoid(c2[2]) * c2[3]),
;                                pack2(c3[0] * fsigmoid(c3[0]) * c3[1], c3[2] * fsigmoid(c3[2]) * c3[3]));
;     *(uint4*)(Hh + (size_t)row * FH + (cb >> 1) + q4 * 8) = o;
;   };
	v_mfma_f32_16x16x32_bf16 v[30:33], v[130:133], v[110:113], v[30:33]
	v_mfma_f32_16x16x32_bf16 v[26:29], v[134:137], v[110:113], v[26:29]
	v_mfma_f32_16x16x32_bf16 v[22:25], v[146:149], v[110:113], v[22:25]
	v_mfma_f32_16x16x32_bf16 v[18:21], v[150:153], v[110:113], v[18:21]
	s_waitcnt lgkmcnt(0)
	v_mfma_f32_16x16x32_bf16 v[14:17], v[130:133], v[106:109], v[14:17]
	v_mfma_f32_16x16x32_bf16 v[10:13], v[134:137], v[106:109], v[10:13]
	v_mfma_f32_16x16x32_bf16 v[6:9], v[146:149], v[106:109], v[6:9]
	v_mfma_f32_16x16x32_bf16 v[2:5], v[150:153], v[106:109], v[2:5]
	v_or_b32_e32 v107, s38, v142
	v_lshl_add_u32 v110, v141, 7, v107
	v_mul_f32_e32 v107, 0xbfb8aa3b, v126
	v_mul_f32_e32 v108, 0xbfb8aa3b, v128
	v_exp_f32_e32 v107, v107
	v_exp_f32_e32 v109, v108
	v_lshl_or_b32 v106, v143, 6, s39
	v_ashrrev_i32_e32 v108, 1, v106
	v_add_f32_e32 v106, 1.0, v107
	v_add_f32_e32 v107, 1.0, v109
	v_rcp_f32_e32 v106, v106
	v_rcp_f32_e32 v107, v107
	v_mov_b32_e32 v112, v126
	v_mov_b32_e32 v113, v128
	v_mul_f32_e32 v111, 0xbfb8aa3b, v122
	v_pk_mul_f32 v[106:107], v[112:113], v[106:107]
	v_exp_f32_e32 v111, v111
	v_mul_f32_e32 v112, 0xbfb8aa3b, v124
	v_exp_f32_e32 v113, v112
	v_mov_b32_e32 v128, v127
	v_add_f32_e32 v111, 1.0, v111
	v_rcp_f32_e32 v112, v111
	v_add_f32_e32 v111, 1.0, v113
	v_rcp_f32_e32 v113, v111
	v_pk_mul_f32 v[106:107], v[128:129], v[106:107]
	v_mul_f32_e32 v111, 0xbfb8aa3b, v118
	v_cvt_pk_bf16_f32 v126, v106, v107
	v_mov_b32_e32 v106, v122
	v_mov_b32_e32 v107, v124
	v_pk_mul_f32 v[106:107], v[106:107], v[112:113]
	v_exp_f32_e32 v111, v111
	v_mul_f32_e32 v112, 0xbfb8aa3b, v120
	v_exp_f32_e32 v113, v112
	v_mov_b32_e32 v124, v123
	v_add_f32_e32 v111, 1.0, v111
	v_rcp_f32_e32 v112, v111
	v_add_f32_e32 v111, 1.0, v113
	v_rcp_f32_e32 v113, v111
	v_pk_mul_f32 v[106:107], v[124:125], v[106:107]
	v_mul_f32_e32 v111, 0xbfb8aa3b, v114
	v_cvt_pk_bf16_f32 v127, v106, v107
	v_mov_b32_e32 v106, v118
	v_mov_b32_e32 v107, v120
	v_pk_mul_f32 v[106:107], v[106:107], v[112:113]
	v_exp_f32_e32 v111, v111
	v_mul_f32_e32 v112, 0xbfb8aa3b, v116
	v_exp_f32_e32 v113, v112
	v_mov_b32_e32 v120, v119
	v_add_f32_e32 v111, 1.0, v111
	v_rcp_f32_e32 v112, v111
	v_add_f32_e32 v111, 1.0, v113
	v_rcp_f32_e32 v113, v111
	v_pk_mul_f32 v[106:107], v[120:121], v[106:107]
	v_readlane_b32 s52, v253, 40
	v_cvt_pk_bf16_f32 v128, v106, v107
	v_mov_b32_e32 v106, v114
	v_mov_b32_e32 v107, v116
	v_pk_mul_f32 v[106:107], v[106:107], v[112:113]
	v_mov_b32_e32 v116, v115
	v_mul_f32_e32 v111, 0xbfb8aa3b, v162
	v_pk_mul_f32 v[106:107], v[116:117], v[106:107]
	v_readlane_b32 s54, v253, 42
	v_readlane_b32 s55, v253, 43
	v_exp_f32_e32 v111, v111
	v_mul_f32_e32 v114, 0xbfb8aa3b, v164
	v_ashrrev_i32_e32 v109, 31, v108
	v_cvt_pk_bf16_f32 v129, v106, v107
	v_mov_b64_e32 v[106:107], s[54:55]
	s_movk_i32 s38, 0x1600
	v_exp_f32_e32 v114, v114
	v_mad_i64_i32 v[112:113], s[16:17], v110, s38, v[106:107]
	v_lshlrev_b64 v[108:109], 1, v[108:109]
	v_lshl_add_u64 v[112:113], v[112:113], 0, v[108:109]
	v_lshlrev_b32_e32 v190, 4, v140
	v_lshl_add_u64 v[112:113], v[112:113], 0, v[190:191]
	v_add_f32_e32 v111, 1.0, v111
	s_waitcnt vmcnt(0)
	s_barrier
	global_store_dwordx4 v[112:113], v[126:129], off
	v_rcp_f32_e32 v112, v111
	v_add_f32_e32 v111, 1.0, v114
	v_rcp_f32_e32 v113, v111
	v_mov_b32_e32 v114, v162
	v_mov_b32_e32 v115, v164
	v_mov_b32_e32 v164, v163
	v_pk_mul_f32 v[112:113], v[114:115], v[112:113]
	v_mul_f32_e32 v114, 0xbfb8aa3b, v166
	v_mul_f32_e32 v115, 0xbfb8aa3b, v168
	v_exp_f32_e32 v114, v114
	v_exp_f32_e32 v115, v115
	v_pk_mul_f32 v[112:113], v[164:165], v[112:113]
	v_mov_b32_e32 v116, v166
	v_add_f32_e32 v114, 1.0, v114
	v_add_f32_e32 v115, 1.0, v115
	v_rcp_f32_e32 v114, v114
	v_rcp_f32_e32 v115, v115
	v_cvt_pk_bf16_f32 v112, v112, v113
	v_mov_b32_e32 v117, v168
	v_mul_f32_e32 v113, 0xbfb8aa3b, v102
	v_pk_mul_f32 v[114:115], v[116:117], v[114:115]
	v_exp_f32_e32 v113, v113
	v_mul_f32_e32 v116, 0xbfb8aa3b, v104
	v_exp_f32_e32 v117, v116
	v_mov_b32_e32 v168, v167
	v_add_f32_e32 v113, 1.0, v113
	v_rcp_f32_e32 v116, v113
	v_add_f32_e32 v113, 1.0, v117
	v_rcp_f32_e32 v117, v113
	v_pk_mul_f32 v[114:115], v[168:169], v[114:115]
	v_or_b32_e32 v111, 16, v110
	v_cvt_pk_bf16_f32 v113, v114, v115
	v_mov_b32_e32 v114, v102
	v_mov_b32_e32 v115, v104
	v_mul_f32_e32 v102, 0xbfb8aa3b, v98
	v_pk_mul_f32 v[114:115], v[114:115], v[116:117]
	v_exp_f32_e32 v116, v102
	v_mul_f32_e32 v102, 0xbfb8aa3b, v100
	v_exp_f32_e32 v117, v102
	v_mov_b32_e32 v104, v103
	v_pk_mul_f32 v[102:103], v[104:105], v[114:115]
	v_add_f32_e32 v104, 1.0, v116
	v_add_f32_e32 v105, 1.0, v117
	v_rcp_f32_e32 v104, v104
	v_rcp_f32_e32 v105, v105
	v_cvt_pk_bf16_f32 v114, v102, v103
	v_mov_b32_e32 v102, v98
	v_mov_b32_e32 v103, v100
	v_pk_mul_f32 v[102:103], v[102:103], v[104:105]
	v_mov_b32_e32 v100, v99
	v_pk_mul_f32 v[98:99], v[100:101], v[102:103]
	v_mul_f32_e32 v100, 0xbfb8aa3b, v94
	v_mul_f32_e32 v101, 0xbfb8aa3b, v96
	v_exp_f32_e32 v100, v100
	v_exp_f32_e32 v101, v101
	v_cvt_pk_bf16_f32 v115, v98, v99
	v_mad_i64_i32 v[98:99], s[16:17], v111, s38, v[106:107]
	v_lshl_add_u64 v[98:99], v[98:99], 0, v[108:109]
	v_lshl_add_u64 v[98:99], v[98:99], 0, v[190:191]
	global_store_dwordx4 v[98:99], v[112:115], off
	v_add_f32_e32 v98, 1.0, v100
	v_add_f32_e32 v99, 1.0, v101
	v_rcp_f32_e32 v98, v98
	v_rcp_f32_e32 v99, v99
	v_mov_b32_e32 v100, v94
	v_mov_b32_e32 v101, v96
	v_mul_f32_e32 v94, 0xbfb8aa3b, v90
	v_pk_mul_f32 v[98:99], v[100:101], v[98:99]
	v_exp_f32_e32 v100, v94
	v_mul_f32_e32 v94, 0xbfb8aa3b, v92
	v_exp_f32_e32 v101, v94
	v_mov_b32_e32 v96, v95
	v_pk_mul_f32 v[94:95], v[96:97], v[98:99]
	v_add_f32_e32 v96, 1.0, v100
	v_add_f32_e32 v97, 1.0, v101
; DI unsigned pack2(float a, float b) { hwf2_t f = {a, b}; return __builtin_bit_cast(unsigned, __builtin_convertvector(f, hwbf2_t)); }
; DI float fsigmoid(float x) { return __builtin_amdgcn_rcpf(1.f + __expf(-x)); }
; DI void phase_ffn_up(char* smem, const Params& p, int layer) {
;     ...
;   auto ep = [=](int row, int cb, int q4, const f32x4& c0, const f32x4& c1, const f32x4& c2, const f32x4& c3) {
;     const uint4 o = make_uint4(pack2(c0[0] * fsigmoid(c0[0]) * c0[1], c0[2] * fsigmoid(c0[2]) * c0[3]),
;                                pack2(c1[0] * fsigmoid(c1[0]) * c1[1], c1[2] * fsigmoid(c1[2]) * c1[3]),
;                                pack2(c2[0] * fsigmoid(c2[0]) * c2[1], c2[2] * fsigmoid(c2[2]) * c2[3]),
;                                pack2(c3[0] * fsigmoid(c3[0]) * c3[1], c3[2] * fsigmoid(c3[2]) * c3[3]));
;     *(uint4*)(Hh + (size_t)row * FH + (cb >> 1) + q4 * 8) = o;
;   };
	v_rcp_f32_e32 v96, v96
	v_rcp_f32_e32 v97, v97
	v_mov_b32_e32 v98, v90
	v_mul_f32_e32 v90, 0xbfb8aa3b, v86
	v_cvt_pk_bf16_f32 v94, v94, v95
	v_mov_b32_e32 v99, v92
	v_exp_f32_e32 v95, v90
	v_mul_f32_e32 v90, 0xbfb8aa3b, v88
	v_pk_mul_f32 v[96:97], v[98:99], v[96:97]
	v_exp_f32_e32 v98, v90
	v_mov_b32_e32 v92, v91
	v_pk_mul_f32 v[90:91], v[92:93], v[96:97]
	v_add_f32_e32 v92, 1.0, v95
	v_add_f32_e32 v93, 1.0, v98
	v_rcp_f32_e32 v92, v92
	v_rcp_f32_e32 v93, v93
	v_cvt_pk_bf16_f32 v95, v90, v91
	v_mov_b32_e32 v90, v86
	v_mov_b32_e32 v91, v88
	v_mul_f32_e32 v86, 0xbfb8aa3b, v82
	v_pk_mul_f32 v[90:91], v[90:91], v[92:93]
	v_exp_f32_e32 v92, v86
	v_mul_f32_e32 v86, 0xbfb8aa3b, v84
	v_exp_f32_e32 v93, v86
	v_mov_b32_e32 v88, v87
	v_pk_mul_f32 v[86:87], v[88:89], v[90:91]
	v_add_f32_e32 v88, 1.0, v92
	v_add_f32_e32 v89, 1.0, v93
	v_rcp_f32_e32 v88, v88
	v_rcp_f32_e32 v89, v89
	v_cvt_pk_bf16_f32 v96, v86, v87
	v_mov_b32_e32 v86, v82
	v_mov_b32_e32 v87, v84
	v_pk_mul_f32 v[86:87], v[86:87], v[88:89]
	v_mov_b32_e32 v84, v83
	v_pk_mul_f32 v[82:83], v[84:85], v[86:87]
	v_mul_f32_e32 v84, 0xbfb8aa3b, v78
	v_mul_f32_e32 v85, 0xbfb8aa3b, v80
	v_or_b32_e32 v102, 32, v110
	v_exp_f32_e32 v84, v84
	v_exp_f32_e32 v85, v85
	v_cvt_pk_bf16_f32 v97, v82, v83
	v_mad_i64_i32 v[82:83], s[16:17], v102, s38, v[106:107]
	v_lshl_add_u64 v[82:83], v[82:83], 0, v[108:109]
	v_lshl_add_u64 v[82:83], v[82:83], 0, v[190:191]
	global_store_dwordx4 v[82:83], v[94:97], off
	v_add_f32_e32 v82, 1.0, v84
	v_add_f32_e32 v83, 1.0, v85
	v_rcp_f32_e32 v82, v82
	v_rcp_f32_e32 v83, v83
	v_mov_b32_e32 v84, v78
	v_mov_b32_e32 v85, v80
	v_mul_f32_e32 v78, 0xbfb8aa3b, v74
	v_pk_mul_f32 v[82:83], v[84:85], v[82:83]
	v_exp_f32_e32 v84, v78
	v_mul_f32_e32 v78, 0xbfb8aa3b, v76
	v_exp_f32_e32 v85, v78
	v_mov_b32_e32 v80, v79
	v_pk_mul_f32 v[78:79], v[80:81], v[82:83]
	v_add_f32_e32 v80, 1.0, v84
	v_add_f32_e32 v81, 1.0, v85
	v_rcp_f32_e32 v80, v80
	v_rcp_f32_e32 v81, v81
	v_mov_b32_e32 v82, v74
	v_mul_f32_e32 v74, 0xbfb8aa3b, v70
	v_cvt_pk_bf16_f32 v78, v78, v79
	v_mov_b32_e32 v83, v76
	v_exp_f32_e32 v79, v74
	v_mul_f32_e32 v74, 0xbfb8aa3b, v72
	v_pk_mul_f32 v[80:81], v[82:83], v[80:81]
	v_exp_f32_e32 v82, v74
	v_mov_b32_e32 v76, v75
	v_pk_mul_f32 v[74:75], v[76:77], v[80:81]
	v_add_f32_e32 v76, 1.0, v79
	v_add_f32_e32 v77, 1.0, v82
	v_rcp_f32_e32 v76, v76
	v_rcp_f32_e32 v77, v77
	v_cvt_pk_bf16_f32 v79, v74, v75
	v_mov_b32_e32 v74, v70
	v_mov_b32_e32 v75, v72
	v_mul_f32_e32 v70, 0xbfb8aa3b, v66
	v_pk_mul_f32 v[74:75], v[74:75], v[76:77]
	v_exp_f32_e32 v76, v70
	v_mul_f32_e32 v70, 0xbfb8aa3b, v68
	v_exp_f32_e32 v77, v70
	v_mov_b32_e32 v72, v71
	v_pk_mul_f32 v[70:71], v[72:73], v[74:75]
	v_add_f32_e32 v72, 1.0, v76
	v_add_f32_e32 v73, 1.0, v77
	v_rcp_f32_e32 v72, v72
	v_rcp_f32_e32 v73, v73
	v_cvt_pk_bf16_f32 v80, v70, v71
	v_mov_b32_e32 v70, v66
	v_mov_b32_e32 v71, v68
	v_pk_mul_f32 v[70:71], v[70:71], v[72:73]
	v_mov_b32_e32 v68, v67
	v_pk_mul_f32 v[66:67], v[68:69], v[70:71]
	v_mul_f32_e32 v68, 0xbfb8aa3b, v62
	v_mul_f32_e32 v69, 0xbfb8aa3b, v64
	v_or_b32_e32 v86, 48, v110
	v_exp_f32_e32 v68, v68
	v_exp_f32_e32 v69, v69
	v_cvt_pk_bf16_f32 v81, v66, v67
	v_mad_i64_i32 v[66:67], s[16:17], v86, s38, v[106:107]
	v_lshl_add_u64 v[66:67], v[66:67], 0, v[108:109]
	v_lshl_add_u64 v[66:67], v[66:67], 0, v[190:191]
	global_store_dwordx4 v[66:67], v[78:81], off
	v_add_f32_e32 v66, 1.0, v68
	v_add_f32_e32 v67, 1.0, v69
	v_rcp_f32_e32 v66, v66
	v_rcp_f32_e32 v67, v67
	v_mov_b32_e32 v68, v62
	v_mov_b32_e32 v69, v64
	v_mul_f32_e32 v62, 0xbfb8aa3b, v58
	v_pk_mul_f32 v[66:67], v[68:69], v[66:67]
	v_exp_f32_e32 v68, v62
	v_mul_f32_e32 v62, 0xbfb8aa3b, v60
	v_exp_f32_e32 v69, v62
	v_mov_b32_e32 v64, v63
	v_pk_mul_f32 v[62:63], v[64:65], v[66:67]
	v_add_f32_e32 v64, 1.0, v68
	v_add_f32_e32 v65, 1.0, v69
	v_rcp_f32_e32 v64, v64
	v_rcp_f32_e32 v65, v65
	v_mov_b32_e32 v66, v58
	v_mul_f32_e32 v58, 0xbfb8aa3b, v54
	v_cvt_pk_bf16_f32 v62, v62, v63
	v_mov_b32_e32 v67, v60
	v_exp_f32_e32 v63, v58
	v_mul_f32_e32 v58, 0xbfb8aa3b, v56
	v_pk_mul_f32 v[64:65], v[66:67], v[64:65]
	v_exp_f32_e32 v66, v58
	v_mov_b32_e32 v60, v59
	v_pk_mul_f32 v[58:59], v[60:61], v[64:65]
	v_add_f32_e32 v60, 1.0, v63
	v_add_f32_e32 v61, 1.0, v66
	v_rcp_f32_e32 v60, v60
	v_rcp_f32_e32 v61, v61
	v_cvt_pk_bf16_f32 v63, v58, v59
	v_mov_b32_e32 v58, v54
	v_mov_b32_e32 v59, v56
	v_mul_f32_e32 v54, 0xbfb8aa3b, v50
	v_pk_mul_f32 v[58:59], v[58:59], v[60:61]
	v_exp_f32_e32 v60, v54
	v_mul_f32_e32 v54, 0xbfb8aa3b, v52
	v_exp_f32_e32 v61, v54
	v_mov_b32_e32 v56, v55
	v_pk_mul_f32 v[54:55], v[56:57], v[58:59]
	v_add_f32_e32 v56, 1.0, v60
	v_add_f32_e32 v57, 1.0, v61
	v_rcp_f32_e32 v56, v56
	v_rcp_f32_e32 v57, v57
	v_cvt_pk_bf16_f32 v64, v54, v55
	v_mov_b32_e32 v54, v50
	v_mov_b32_e32 v55, v52
	v_pk_mul_f32 v[54:55], v[54:55], v[56:57]
	v_mov_b32_e32 v52, v51
	v_pk_mul_f32 v[50:51], v[52:53], v[54:55]
	v_mul_f32_e32 v52, 0xbfb8aa3b, v46
	v_mul_f32_e32 v53, 0xbfb8aa3b, v48
	v_or_b32_e32 v70, 64, v110
	v_exp_f32_e32 v52, v52
	v_exp_f32_e32 v53, v53
	v_cvt_pk_bf16_f32 v65, v50, v51
	v_mad_i64_i32 v[50:51], s[16:17], v70, s38, v[106:107]
	v_lshl_add_u64 v[50:51], v[50:51], 0, v[108:109]
	v_lshl_add_u64 v[50:51], v[50:51], 0, v[190:191]
	global_store_dwordx4 v[50:51], v[62:65], off
	v_add_f32_e32 v50, 1.0, v52
	v_add_f32_e32 v51, 1.0, v53
	v_rcp_f32_e32 v50, v50
	v_rcp_f32_e32 v51, v51
	v_mov_b32_e32 v52, v46
	v_mov_b32_e32 v53, v48
	v_mul_f32_e32 v46, 0xbfb8aa3b, v42
	v_pk_mul_f32 v[50:51], v[52:53], v[50:51]
	v_exp_f32_e32 v52, v46
	v_mul_f32_e32 v46, 0xbfb8aa3b, v44
	v_exp_f32_e32 v53, v46
	v_mov_b32_e32 v48, v47
	v_pk_mul_f32 v[46:47], v[48:49], v[50:51]
; DI unsigned pack2(float a, float b) { hwf2_t f = {a, b}; return __builtin_bit_cast(unsigned, __builtin_convertvector(f, hwbf2_t)); }
; DI float fsigmoid(float x) { return __builtin_amdgcn_rcpf(1.f + __expf(-x)); }
; DI void phase_ffn_up(char* smem, const Params& p, int layer) {
;     ...
;   auto ep = [=](int row, int cb, int q4, const f32x4& c0, const f32x4& c1, const f32x4& c2, const f32x4& c3) {
;     const uint4 o = make_uint4(pack2(c0[0] * fsigmoid(c0[0]) * c0[1], c0[2] * fsigmoid(c0[2]) * c0[3]),
;                                pack2(c1[0] * fsigmoid(c1[0]) * c1[1], c1[2] * fsigmoid(c1[2]) * c1[3]),
;                                pack2(c2[0] * fsigmoid(c2[0]) * c2[1], c2[2] * fsigmoid(c2[2]) * c2[3]),
;                                pack2(c3[0] * fsigmoid(c3[0]) * c3[1], c3[2] * fsigmoid(c3[2]) * c3[3]));
;     *(uint4*)(Hh + (size_t)row * FH + (cb >> 1) + q4 * 8) = o;
;   };
	v_add_f32_e32 v48, 1.0, v52
	v_add_f32_e32 v49, 1.0, v53
	v_rcp_f32_e32 v48, v48
	v_rcp_f32_e32 v49, v49
	v_mov_b32_e32 v50, v42
	v_mul_f32_e32 v42, 0xbfb8aa3b, v38
	v_cvt_pk_bf16_f32 v46, v46, v47
	v_mov_b32_e32 v51, v44
	v_exp_f32_e32 v47, v42
	v_mul_f32_e32 v42, 0xbfb8aa3b, v40
	v_pk_mul_f32 v[48:49], v[50:51], v[48:49]
	v_exp_f32_e32 v50, v42
	v_mov_b32_e32 v44, v43
	v_pk_mul_f32 v[42:43], v[44:45], v[48:49]
	v_add_f32_e32 v44, 1.0, v47
	v_add_f32_e32 v45, 1.0, v50
	v_rcp_f32_e32 v44, v44
	v_rcp_f32_e32 v45, v45
	v_cvt_pk_bf16_f32 v47, v42, v43
	v_mov_b32_e32 v42, v38
	v_mov_b32_e32 v43, v40
	v_mul_f32_e32 v38, 0xbfb8aa3b, v34
	v_pk_mul_f32 v[42:43], v[42:43], v[44:45]
	v_exp_f32_e32 v44, v38
	v_mul_f32_e32 v38, 0xbfb8aa3b, v36
	v_exp_f32_e32 v45, v38
	v_mov_b32_e32 v40, v39
	v_pk_mul_f32 v[38:39], v[40:41], v[42:43]
	v_add_f32_e32 v40, 1.0, v44
	v_add_f32_e32 v41, 1.0, v45
	v_rcp_f32_e32 v40, v40
	v_rcp_f32_e32 v41, v41
	v_cvt_pk_bf16_f32 v48, v38, v39
	v_mov_b32_e32 v38, v34
	v_mov_b32_e32 v39, v36
	v_pk_mul_f32 v[38:39], v[38:39], v[40:41]
	v_mov_b32_e32 v36, v35
	v_pk_mul_f32 v[34:35], v[36:37], v[38:39]
	v_mul_f32_e32 v36, 0xbfb8aa3b, v30
	v_mul_f32_e32 v37, 0xbfb8aa3b, v32
	v_or_b32_e32 v54, 0x50, v110
	v_exp_f32_e32 v36, v36
	v_exp_f32_e32 v37, v37
	v_cvt_pk_bf16_f32 v49, v34, v35
	v_mad_i64_i32 v[34:35], s[16:17], v54, s38, v[106:107]
	v_lshl_add_u64 v[34:35], v[34:35], 0, v[108:109]
	v_lshl_add_u64 v[34:35], v[34:35], 0, v[190:191]
	global_store_dwordx4 v[34:35], v[46:49], off
	v_add_f32_e32 v34, 1.0, v36
	v_add_f32_e32 v35, 1.0, v37
	v_rcp_f32_e32 v34, v34
	v_rcp_f32_e32 v35, v35
	v_mov_b32_e32 v36, v30
	v_mov_b32_e32 v37, v32
	v_mul_f32_e32 v30, 0xbfb8aa3b, v26
	v_pk_mul_f32 v[34:35], v[36:37], v[34:35]
	v_exp_f32_e32 v36, v30
	v_mul_f32_e32 v30, 0xbfb8aa3b, v28
	v_exp_f32_e32 v37, v30
	v_mov_b32_e32 v32, v31
	v_pk_mul_f32 v[30:31], v[32:33], v[34:35]
	v_add_f32_e32 v32, 1.0, v36
	v_add_f32_e32 v33, 1.0, v37
	v_rcp_f32_e32 v32, v32
	v_rcp_f32_e32 v33, v33
	v_mov_b32_e32 v34, v26
	v_mul_f32_e32 v26, 0xbfb8aa3b, v22
	v_cvt_pk_bf16_f32 v30, v30, v31
	v_mov_b32_e32 v35, v28
	v_exp_f32_e32 v31, v26
	v_mul_f32_e32 v26, 0xbfb8aa3b, v24
	v_pk_mul_f32 v[32:33], v[34:35], v[32:33]
	v_exp_f32_e32 v34, v26
	v_mov_b32_e32 v28, v27
	v_pk_mul_f32 v[26:27], v[28:29], v[32:33]
	v_add_f32_e32 v28, 1.0, v31
	v_add_f32_e32 v29, 1.0, v34
	v_rcp_f32_e32 v28, v28
	v_rcp_f32_e32 v29, v29
	v_cvt_pk_bf16_f32 v31, v26, v27
	v_mov_b32_e32 v26, v22
	v_mov_b32_e32 v27, v24
	v_mul_f32_e32 v22, 0xbfb8aa3b, v18
	v_pk_mul_f32 v[26:27], v[26:27], v[28:29]
	v_exp_f32_e32 v28, v22
	v_mul_f32_e32 v22, 0xbfb8aa3b, v20
	v_exp_f32_e32 v29, v22
	v_mov_b32_e32 v24, v23
	v_pk_mul_f32 v[22:23], v[24:25], v[26:27]
	v_add_f32_e32 v24, 1.0, v28
	v_add_f32_e32 v25, 1.0, v29
	v_rcp_f32_e32 v24, v24
	v_rcp_f32_e32 v25, v25
	v_cvt_pk_bf16_f32 v32, v22, v23
	v_mov_b32_e32 v22, v18
	v_mov_b32_e32 v23, v20
	v_pk_mul_f32 v[22:23], v[22:23], v[24:25]
	v_mov_b32_e32 v20, v19
	v_pk_mul_f32 v[18:19], v[20:21], v[22:23]
	v_mul_f32_e32 v20, 0xbfb8aa3b, v14
	v_mul_f32_e32 v21, 0xbfb8aa3b, v16
	v_or_b32_e32 v38, 0x60, v110
	v_exp_f32_e32 v20, v20
	v_exp_f32_e32 v21, v21
	v_cvt_pk_bf16_f32 v33, v18, v19
	v_mad_i64_i32 v[18:19], s[16:17], v38, s38, v[106:107]
	v_lshl_add_u64 v[18:19], v[18:19], 0, v[108:109]
	v_lshl_add_u64 v[18:19], v[18:19], 0, v[190:191]
	global_store_dwordx4 v[18:19], v[30:33], off
	v_add_f32_e32 v18, 1.0, v20
	v_add_f32_e32 v19, 1.0, v21
	v_rcp_f32_e32 v18, v18
	v_rcp_f32_e32 v19, v19
	v_mov_b32_e32 v20, v14
	v_mov_b32_e32 v21, v16
	v_mul_f32_e32 v14, 0xbfb8aa3b, v10
	v_pk_mul_f32 v[18:19], v[20:21], v[18:19]
	v_exp_f32_e32 v20, v14
	v_mul_f32_e32 v14, 0xbfb8aa3b, v12
	v_exp_f32_e32 v21, v14
	v_mov_b32_e32 v16, v15
	v_pk_mul_f32 v[14:15], v[16:17], v[18:19]
	v_add_f32_e32 v16, 1.0, v20
	v_add_f32_e32 v17, 1.0, v21
	v_rcp_f32_e32 v16, v16
	v_rcp_f32_e32 v17, v17
	v_mov_b32_e32 v18, v10
	v_mul_f32_e32 v10, 0xbfb8aa3b, v6
	v_cvt_pk_bf16_f32 v14, v14, v15
	v_mov_b32_e32 v19, v12
	v_exp_f32_e32 v15, v10
	v_mul_f32_e32 v10, 0xbfb8aa3b, v8
	v_pk_mul_f32 v[16:17], v[18:19], v[16:17]
	v_exp_f32_e32 v18, v10
	v_mov_b32_e32 v12, v11
	v_pk_mul_f32 v[10:11], v[12:13], v[16:17]
	v_add_f32_e32 v12, 1.0, v15
	v_add_f32_e32 v13, 1.0, v18
	v_rcp_f32_e32 v12, v12
	v_rcp_f32_e32 v13, v13
	v_cvt_pk_bf16_f32 v15, v10, v11
	v_mov_b32_e32 v10, v6
	v_mov_b32_e32 v11, v8
	v_mul_f32_e32 v6, 0xbfb8aa3b, v2
	v_pk_mul_f32 v[10:11], v[10:11], v[12:13]
	v_exp_f32_e32 v12, v6
	v_mul_f32_e32 v6, 0xbfb8aa3b, v4
	v_exp_f32_e32 v13, v6
	v_mov_b32_e32 v8, v7
	v_pk_mul_f32 v[6:7], v[8:9], v[10:11]
	v_add_f32_e32 v8, 1.0, v12
	v_add_f32_e32 v9, 1.0, v13
	v_rcp_f32_e32 v8, v8
	v_rcp_f32_e32 v9, v9
	v_cvt_pk_bf16_f32 v16, v6, v7
	v_mov_b32_e32 v6, v2
	v_mov_b32_e32 v7, v4
	v_pk_mul_f32 v[6:7], v[6:7], v[8:9]
	v_mov_b32_e32 v4, v3
	v_or_b32_e32 v22, 0x70, v110
	v_pk_mul_f32 v[2:3], v[4:5], v[6:7]
	s_add_i32 s37, s37, s30
	v_cvt_pk_bf16_f32 v17, v2, v3
	v_mad_i64_i32 v[2:3], s[16:17], v22, s38, v[106:107]
	v_lshl_add_u64 v[2:3], v[2:3], 0, v[108:109]
	s_cmp_gt_i32 s37, 31
	v_lshl_add_u64 v[2:3], v[2:3], 0, v[190:191]
	s_cselect_b64 s[16:17], -1, 0
	v_readlane_b32 s53, v253, 41
	v_readlane_b32 s56, v253, 44
	v_readlane_b32 s57, v253, 45
	v_readlane_b32 s58, v253, 46
	v_readlane_b32 s59, v253, 47
	v_readlane_b32 s60, v253, 48
	v_readlane_b32 s61, v253, 49
	v_readlane_b32 s62, v253, 50
	v_readlane_b32 s63, v253, 51
	v_readlane_b32 s64, v253, 52
	v_readlane_b32 s65, v253, 53
	v_readlane_b32 s66, v253, 54
	v_readlane_b32 s67, v253, 55
	global_store_dwordx4 v[2:3], v[14:17], off
	s_branch .LBB0_68

; #define MFMA16(a, b, c) __builtin_amdgcn_mfma_f32_16x16x32_bf16((a), (b), (c), 0, 0, 0)
;     ...
;   for (int kt = 0; kt < nk; ++kt) {
;     const int buf = kt & 1;
;     const char* cA = smem + buf * STAGE + (wm * 32 * MI + r16) * 128;
;     const char* cB = smem + buf * STAGE + 32768 + (wn * 64 + r16) * 128;
; #pragma unroll
;     for (int k2 = 0; k2 < 2; ++k2) {
;       if (k2 == 1 && kt + 1 < nk) STAGE_TILE(buf ^ 1, (kt + 1) * 64)
;       const int po = ((4 * k2 + q4) ^ swz) * 16;
;       bf16x8 bf[4];
; #pragma unroll
;       for (int nt = 0; nt < 4; ++nt) bf[nt] = *(const bf16x8*)(cB + nt * 16 * 128 + po);
;       bf16x8 afc = *(const bf16x8*)(cA + po);
; #pragma unroll
;       for (int a = 0; a < MT; ++a) {
;         bf16x8 afn = afc;
;         if (a + 1 < MT) afn = *(const bf16x8*)(cA + (a + 1) * 16 * 128 + po);
;         __builtin_amdgcn_sched_barrier(0);
; #pragma unroll
;         for (int nt = 0; nt < 4; ++nt) acc[a][nt] = MFMA16(bf[nt], afc, acc[a][nt]);
;         __builtin_amdgcn_sched_barrier(0);
;         afc = afn;
;       }
;     }
;     asm volatile("s_waitcnt vmcnt(0)" ::: "memory");
;     __syncthreads();
;   }
.LBB0_107:
	s_and_b32 s46, s45, 0x10000
	s_add_i32 s47, s46, 0
	s_xor_b32 s46, s46, 0x10000
	v_add_u32_e32 v174, s47, v147
	v_add_u32_e32 v162, v174, v146
	v_add_u32_e32 v149, s47, v148
	v_add_u32_e32 v175, v149, v146
	ds_read_b128 v[150:153], v162 offset:32768
	ds_read_b128 v[166:169], v175
	ds_read_b128 v[154:157], v162 offset:34816
	ds_read_b128 v[158:161], v162 offset:36864
	ds_read_b128 v[162:165], v162 offset:38912
	ds_read_b128 v[170:173], v175 offset:2048
	s_waitcnt lgkmcnt(4)
	v_mfma_f32_16x16x32_bf16 v[126:129], v[150:153], v[166:169], v[126:129]
	v_readfirstlane_b32 s47, v145
	s_waitcnt lgkmcnt(3)
	v_mfma_f32_16x16x32_bf16 v[122:125], v[154:157], v[166:169], v[122:125]
	s_nop 0
	s_waitcnt lgkmcnt(2)
	v_mfma_f32_16x16x32_bf16 v[118:121], v[158:161], v[166:169], v[118:121]
	s_add_u32 s47, s47, s46
	s_waitcnt lgkmcnt(1)
	v_mfma_f32_16x16x32_bf16 v[114:117], v[162:165], v[166:169], v[114:117]
	ds_read_b128 v[166:169], v175 offset:4096
	s_add_u32 m0, s47, 0x0
	s_waitcnt lgkmcnt(1)
	v_mfma_f32_16x16x32_bf16 v[110:113], v[150:153], v[170:173], v[110:113]
	global_load_lds_dwordx4 v176, s[100:101]
	v_mfma_f32_16x16x32_bf16 v[106:109], v[154:157], v[170:173], v[106:109]
	s_add_u32 m0, s47, 0x2000
	v_mfma_f32_16x16x32_bf16 v[102:105], v[158:161], v[170:173], v[102:105]
	global_load_lds_dwordx4 v177, s[100:101]
	v_mfma_f32_16x16x32_bf16 v[98:101], v[162:165], v[170:173], v[98:101]
	ds_read_b128 v[170:173], v175 offset:6144
	s_add_u32 m0, s47, 0x4000
	s_waitcnt lgkmcnt(1)
	v_mfma_f32_16x16x32_bf16 v[94:97], v[150:153], v[166:169], v[94:97]
	global_load_lds_dwordx4 v178, s[100:101]
	v_mfma_f32_16x16x32_bf16 v[90:93], v[154:157], v[166:169], v[90:93]
	s_add_u32 m0, s47, 0x6000
	v_mfma_f32_16x16x32_bf16 v[86:89], v[158:161], v[166:169], v[86:89]
	global_load_lds_dwordx4 v179, s[100:101]
	v_mfma_f32_16x16x32_bf16 v[82:85], v[162:165], v[166:169], v[82:85]
	ds_read_b128 v[166:169], v175 offset:8192
	s_add_u32 m0, s47, 0x8000
	s_waitcnt lgkmcnt(1)
	v_mfma_f32_16x16x32_bf16 v[78:81], v[150:153], v[170:173], v[78:81]
	global_load_lds_dwordx4 v180, s[100:101]
	v_mfma_f32_16x16x32_bf16 v[74:77], v[154:157], v[170:173], v[74:77]
	s_add_u32 m0, s47, 0xa000
	v_mfma_f32_16x16x32_bf16 v[70:73], v[158:161], v[170:173], v[70:73]
	global_load_lds_dwordx4 v181, s[100:101]
	v_mfma_f32_16x16x32_bf16 v[66:69], v[162:165], v[170:173], v[66:69]
	ds_read_b128 v[170:173], v175 offset:10240
	s_add_u32 m0, s47, 0xc000
	s_waitcnt lgkmcnt(1)
	v_mfma_f32_16x16x32_bf16 v[62:65], v[150:153], v[166:169], v[62:65]
	global_load_lds_dwordx4 v182, s[100:101]
	v_mfma_f32_16x16x32_bf16 v[58:61], v[154:157], v[166:169], v[58:61]
	s_add_u32 m0, s47, 0xe000
	v_mfma_f32_16x16x32_bf16 v[54:57], v[158:161], v[166:169], v[54:57]
	global_load_lds_dwordx4 v183, s[100:101]
	v_mfma_f32_16x16x32_bf16 v[50:53], v[162:165], v[166:169], v[50:53]
	ds_read_b128 v[166:169], v175 offset:12288
	v_add_u32_e32 v203, v174, v144
	s_waitcnt lgkmcnt(1)
	v_mfma_f32_16x16x32_bf16 v[46:49], v[150:153], v[170:173], v[46:49]
	v_add_u32_e32 v192, v149, v144
	v_mfma_f32_16x16x32_bf16 v[42:45], v[154:157], v[170:173], v[42:45]
	ds_read_b128 v[204:207], v203 offset:32768
	v_mfma_f32_16x16x32_bf16 v[38:41], v[158:161], v[170:173], v[38:41]
	ds_read_b128 v[208:211], v203 offset:34816
	v_mfma_f32_16x16x32_bf16 v[34:37], v[162:165], v[170:173], v[34:37]
	ds_read_b128 v[170:173], v175 offset:14336
	ds_read_b128 v[212:215], v203 offset:36864
	s_waitcnt lgkmcnt(4)
	v_mfma_f32_16x16x32_bf16 v[30:33], v[150:153], v[166:169], v[30:33]
	ds_read_b128 v[216:219], v203 offset:38912
	v_mfma_f32_16x16x32_bf16 v[26:29], v[154:157], v[166:169], v[26:29]
	ds_read_b128 v[220:223], v192
	v_mfma_f32_16x16x32_bf16 v[22:25], v[158:161], v[166:169], v[22:25]
	ds_read_b128 v[198:201], v192 offset:2048
	v_mfma_f32_16x16x32_bf16 v[18:21], v[162:165], v[166:169], v[18:21]
	s_waitcnt lgkmcnt(4)
	v_mfma_f32_16x16x32_bf16 v[14:17], v[150:153], v[170:173], v[14:17]
	v_mfma_f32_16x16x32_bf16 v[10:13], v[154:157], v[170:173], v[10:13]
	v_mfma_f32_16x16x32_bf16 v[6:9], v[158:161], v[170:173], v[6:9]
	v_mfma_f32_16x16x32_bf16 v[2:5], v[162:165], v[170:173], v[2:5]
	s_waitcnt lgkmcnt(1)
	v_mfma_f32_16x16x32_bf16 v[126:129], v[204:207], v[220:223], v[126:129]
	s_add_u32 s100, s100, 0x80
	v_mfma_f32_16x16x32_bf16 v[122:125], v[208:211], v[220:223], v[122:125]
	s_addc_u32 s101, s101, 0
	v_mfma_f32_16x16x32_bf16 v[118:121], v[212:215], v[220:223], v[118:121]
	s_add_u32 s22, s22, 0x80
	v_mfma_f32_16x16x32_bf16 v[114:117], v[216:219], v[220:223], v[114:117]
	ds_read_b128 v[220:223], v192 offset:4096
	s_waitcnt lgkmcnt(1)
	v_mfma_f32_16x16x32_bf16 v[110:113], v[204:207], v[198:201], v[110:113]
	s_addc_u32 s23, s23, 0
	v_mfma_f32_16x16x32_bf16 v[106:109], v[208:211], v[198:201], v[106:109]
	s_add_i32 s45, s45, 0x10000
	v_mfma_f32_16x16x32_bf16 v[102:105], v[212:215], v[198:201], v[102:105]
	v_mfma_f32_16x16x32_bf16 v[98:101], v[216:219], v[198:201], v[98:101]
	ds_read_b128 v[198:201], v192 offset:6144
	s_waitcnt lgkmcnt(1)
	v_mfma_f32_16x16x32_bf16 v[94:97], v[204:207], v[220:223], v[94:97]
	v_mfma_f32_16x16x32_bf16 v[90:93], v[208:211], v[220:223], v[90:93]
	v_mfma_f32_16x16x32_bf16 v[86:89], v[212:215], v[220:223], v[86:89]
	v_mfma_f32_16x16x32_bf16 v[82:85], v[216:219], v[220:223], v[82:85]
	ds_read_b128 v[220:223], v192 offset:8192
	s_waitcnt lgkmcnt(1)
	v_mfma_f32_16x16x32_bf16 v[78:81], v[204:207], v[198:201], v[78:81]
	v_mfma_f32_16x16x32_bf16 v[74:77], v[208:211], v[198:201], v[74:77]
	v_mfma_f32_16x16x32_bf16 v[70:73], v[212:215], v[198:201], v[70:73]
	v_mfma_f32_16x16x32_bf16 v[66:69], v[216:219], v[198:201], v[66:69]
	ds_read_b128 v[198:201], v192 offset:10240
	s_waitcnt lgkmcnt(1)
	v_mfma_f32_16x16x32_bf16 v[62:65], v[204:207], v[220:223], v[62:65]
	v_mfma_f32_16x16x32_bf16 v[58:61], v[208:211], v[220:223], v[58:61]
	v_mfma_f32_16x16x32_bf16 v[54:57], v[212:215], v[220:223], v[54:57]
	v_mfma_f32_16x16x32_bf16 v[50:53], v[216:219], v[220:223], v[50:53]
	ds_read_b128 v[220:223], v192 offset:12288
	s_waitcnt lgkmcnt(1)
	v_mfma_f32_16x16x32_bf16 v[46:49], v[204:207], v[198:201], v[46:49]
	v_mfma_f32_16x16x32_bf16 v[42:45], v[208:211], v[198:201], v[42:45]
	v_mfma_f32_16x16x32_bf16 v[38:41], v[212:215], v[198:201], v[38:41]
	v_mfma_f32_16x16x32_bf16 v[34:37], v[216:219], v[198:201], v[34:37]
	ds_read_b128 v[198:201], v192 offset:14336
	s_waitcnt lgkmcnt(1)
	v_mfma_f32_16x16x32_bf16 v[30:33], v[204:207], v[220:223], v[30:33]
	v_mfma_f32_16x16x32_bf16 v[26:29], v[208:211], v[220:223], v[26:29]
	v_mfma_f32_16x16x32_bf16 v[22:25], v[212:215], v[220:223], v[22:25]
	v_mfma_f32_16x16x32_bf16 v[18:21], v[216:219], v[220:223], v[18:21]
	s_waitcnt lgkmcnt(0)
	v_mfma_f32_16x16x32_bf16 v[14:17], v[204:207], v[198:201], v[14:17]
	v_mfma_f32_16x16x32_bf16 v[10:13], v[208:211], v[198:201], v[10:13]
	v_mfma_f32_16x16x32_bf16 v[6:9], v[212:215], v[198:201], v[6:9]
	v_mfma_f32_16x16x32_bf16 v[2:5], v[216:219], v[198:201], v[2:5]
	s_cmpk_eq_i32 s22, 0x780
	s_waitcnt vmcnt(0)
	s_barrier
	s_cbranch_scc0 .LBB0_107
	s_branch .LBB0_99

; #define MFMA16(a, b, c) __builtin_amdgcn_mfma_f32_16x16x32_bf16((a), (b), (c), 0, 0, 0)
;     ...
;   for (int kt = 0; kt < nk; ++kt) {
;     const int buf = kt & 1;
;     const char* cA = smem + buf * STAGE + (wm * 32 * MI + r16) * 128;
;     const char* cB = smem + buf * STAGE + 32768 + (wn * 64 + r16) * 128;
; #pragma unroll
;     for (int k2 = 0; k2 < 2; ++k2) {
;       if (k2 == 1 && kt + 1 < nk) STAGE_TILE(buf ^ 1, (kt + 1) * 64)
;       const int po = ((4 * k2 + q4) ^ swz) * 16;
;       bf16x8 bf[4];
; #pragma unroll
;       for (int nt = 0; nt < 4; ++nt) bf[nt] = *(const bf16x8*)(cB + nt * 16 * 128 + po);
;       bf16x8 afc = *(const bf16x8*)(cA + po);
; #pragma unroll
;       for (int a = 0; a < MT; ++a) {
;         bf16x8 afn = afc;
;         if (a + 1 < MT) afn = *(const bf16x8*)(cA + (a + 1) * 16 * 128 + po);
;         __builtin_amdgcn_sched_barrier(0);
; #pragma unroll
;         for (int nt = 0; nt < 4; ++nt) acc[a][nt] = MFMA16(bf[nt], afc, acc[a][nt]);
;         __builtin_amdgcn_sched_barrier(0);
;         afc = afn;
;       }
;     }
;     asm volatile("s_waitcnt vmcnt(0)" ::: "memory");
;     __syncthreads();
;   }
.LBB0_565:
	s_and_b32 s6, s5, 0x10000
	s_add_i32 s7, s6, 0
	v_add_u32_e32 v190, s7, v146
	v_add_u32_e32 v164, v190, v145
	v_add_u32_e32 v163, s7, v147
	v_add_u32_e32 v202, v163, v145
	s_xor_b32 s6, s6, 0x10000
	ds_read_b128 v[148:151], v164 offset:32768
	ds_read_b128 v[168:171], v202
	ds_read_b128 v[152:155], v164 offset:34816
	ds_read_b128 v[156:159], v164 offset:36864
	ds_read_b128 v[164:167], v164 offset:38912
	ds_read_b128 v[172:175], v202 offset:2048
	s_waitcnt lgkmcnt(4)
	v_mfma_f32_16x16x32_bf16 v[126:129], v[148:151], v[168:171], v[126:129]
	v_readfirstlane_b32 s7, v144
	s_waitcnt lgkmcnt(3)
	v_mfma_f32_16x16x32_bf16 v[122:125], v[152:155], v[168:171], v[122:125]
	s_nop 0
	s_waitcnt lgkmcnt(2)
	v_mfma_f32_16x16x32_bf16 v[118:121], v[156:159], v[168:171], v[118:121]
	s_add_u32 s7, s7, s6
	s_waitcnt lgkmcnt(1)
	v_mfma_f32_16x16x32_bf16 v[114:117], v[164:167], v[168:171], v[114:117]
	ds_read_b128 v[168:171], v202 offset:4096
	s_add_u32 m0, s7, 0x0
	s_waitcnt lgkmcnt(1)
	v_mfma_f32_16x16x32_bf16 v[110:113], v[148:151], v[172:175], v[110:113]
	global_load_lds_dwordx4 v176, s[100:101]
	v_mfma_f32_16x16x32_bf16 v[106:109], v[152:155], v[172:175], v[106:109]
	s_add_u32 m0, s7, 0x2000
	v_mfma_f32_16x16x32_bf16 v[102:105], v[156:159], v[172:175], v[102:105]
	global_load_lds_dwordx4 v177, s[100:101]
	v_mfma_f32_16x16x32_bf16 v[98:101], v[164:167], v[172:175], v[98:101]
	ds_read_b128 v[172:175], v202 offset:6144
	s_add_u32 m0, s7, 0x4000
	s_waitcnt lgkmcnt(1)
	v_mfma_f32_16x16x32_bf16 v[94:97], v[148:151], v[168:171], v[94:97]
	global_load_lds_dwordx4 v178, s[100:101]
	v_mfma_f32_16x16x32_bf16 v[90:93], v[152:155], v[168:171], v[90:93]
	s_add_u32 m0, s7, 0x6000
	v_mfma_f32_16x16x32_bf16 v[86:89], v[156:159], v[168:171], v[86:89]
	global_load_lds_dwordx4 v179, s[100:101]
	v_mfma_f32_16x16x32_bf16 v[82:85], v[164:167], v[168:171], v[82:85]
	ds_read_b128 v[168:171], v202 offset:8192
	s_add_u32 m0, s7, 0x8000
	s_waitcnt lgkmcnt(1)
	v_mfma_f32_16x16x32_bf16 v[78:81], v[148:151], v[172:175], v[78:81]
	global_load_lds_dwordx4 v180, s[100:101]
	v_mfma_f32_16x16x32_bf16 v[74:77], v[152:155], v[172:175], v[74:77]
	s_add_u32 m0, s7, 0xa000
	v_mfma_f32_16x16x32_bf16 v[70:73], v[156:159], v[172:175], v[70:73]
	global_load_lds_dwordx4 v181, s[100:101]
	v_mfma_f32_16x16x32_bf16 v[66:69], v[164:167], v[172:175], v[66:69]
	ds_read_b128 v[172:175], v202 offset:10240
	s_add_u32 m0, s7, 0xc000
	s_waitcnt lgkmcnt(1)
	v_mfma_f32_16x16x32_bf16 v[62:65], v[148:151], v[168:171], v[62:65]
	global_load_lds_dwordx4 v182, s[100:101]
	v_mfma_f32_16x16x32_bf16 v[58:61], v[152:155], v[168:171], v[58:61]
	s_add_u32 m0, s7, 0xe000
	v_mfma_f32_16x16x32_bf16 v[54:57], v[156:159], v[168:171], v[54:57]
	global_load_lds_dwordx4 v183, s[100:101]
	v_mfma_f32_16x16x32_bf16 v[50:53], v[164:167], v[168:171], v[50:53]
	ds_read_b128 v[168:171], v202 offset:12288
	v_add_u32_e32 v203, v190, v143
	s_waitcnt lgkmcnt(1)
	v_mfma_f32_16x16x32_bf16 v[46:49], v[148:151], v[172:175], v[46:49]
	v_add_u32_e32 v192, v163, v143
	v_mfma_f32_16x16x32_bf16 v[42:45], v[152:155], v[172:175], v[42:45]
	ds_read_b128 v[204:207], v203 offset:32768
	v_mfma_f32_16x16x32_bf16 v[38:41], v[156:159], v[172:175], v[38:41]
	ds_read_b128 v[208:211], v203 offset:34816
	v_mfma_f32_16x16x32_bf16 v[34:37], v[164:167], v[172:175], v[34:37]
	ds_read_b128 v[172:175], v202 offset:14336
	ds_read_b128 v[212:215], v203 offset:36864
	s_waitcnt lgkmcnt(4)
	v_mfma_f32_16x16x32_bf16 v[30:33], v[148:151], v[168:171], v[30:33]
	ds_read_b128 v[216:219], v203 offset:38912
	v_mfma_f32_16x16x32_bf16 v[26:29], v[152:155], v[168:171], v[26:29]
	ds_read_b128 v[220:223], v192
	v_mfma_f32_16x16x32_bf16 v[22:25], v[156:159], v[168:171], v[22:25]
	ds_read_b128 v[198:201], v192 offset:2048
	v_mfma_f32_16x16x32_bf16 v[18:21], v[164:167], v[168:171], v[18:21]
	s_waitcnt lgkmcnt(4)
	v_mfma_f32_16x16x32_bf16 v[14:17], v[148:151], v[172:175], v[14:17]
	v_mfma_f32_16x16x32_bf16 v[10:13], v[152:155], v[172:175], v[10:13]
	v_mfma_f32_16x16x32_bf16 v[6:9], v[156:159], v[172:175], v[6:9]
	v_mfma_f32_16x16x32_bf16 v[2:5], v[164:167], v[172:175], v[2:5]
	s_waitcnt lgkmcnt(1)
	v_mfma_f32_16x16x32_bf16 v[126:129], v[204:207], v[220:223], v[126:129]
	s_add_u32 s100, s100, 0x80
	v_mfma_f32_16x16x32_bf16 v[122:125], v[208:211], v[220:223], v[122:125]
	s_addc_u32 s101, s101, 0
	v_mfma_f32_16x16x32_bf16 v[118:121], v[212:215], v[220:223], v[118:121]
	s_add_u32 s2, s2, 0x80
	v_mfma_f32_16x16x32_bf16 v[114:117], v[216:219], v[220:223], v[114:117]
	ds_read_b128 v[220:223], v192 offset:4096
	s_waitcnt lgkmcnt(1)
	v_mfma_f32_16x16x32_bf16 v[110:113], v[204:207], v[198:201], v[110:113]
	s_addc_u32 s3, s3, 0
	v_mfma_f32_16x16x32_bf16 v[106:109], v[208:211], v[198:201], v[106:109]
	s_add_i32 s5, s5, 0x10000
	v_mfma_f32_16x16x32_bf16 v[102:105], v[212:215], v[198:201], v[102:105]
	v_mfma_f32_16x16x32_bf16 v[98:101], v[216:219], v[198:201], v[98:101]
	ds_read_b128 v[198:201], v192 offset:6144
	s_waitcnt lgkmcnt(1)
	v_mfma_f32_16x16x32_bf16 v[94:97], v[204:207], v[220:223], v[94:97]
	v_mfma_f32_16x16x32_bf16 v[90:93], v[208:211], v[220:223], v[90:93]
	v_mfma_f32_16x16x32_bf16 v[86:89], v[212:215], v[220:223], v[86:89]
	v_mfma_f32_16x16x32_bf16 v[82:85], v[216:219], v[220:223], v[82:85]
	ds_read_b128 v[220:223], v192 offset:8192
	s_waitcnt lgkmcnt(1)
	v_mfma_f32_16x16x32_bf16 v[78:81], v[204:207], v[198:201], v[78:81]
	v_mfma_f32_16x16x32_bf16 v[74:77], v[208:211], v[198:201], v[74:77]
	v_mfma_f32_16x16x32_bf16 v[70:73], v[212:215], v[198:201], v[70:73]
	v_mfma_f32_16x16x32_bf16 v[66:69], v[216:219], v[198:201], v[66:69]
	ds_read_b128 v[198:201], v192 offset:10240
	s_waitcnt lgkmcnt(1)
	v_mfma_f32_16x16x32_bf16 v[62:65], v[204:207], v[220:223], v[62:65]
	v_mfma_f32_16x16x32_bf16 v[58:61], v[208:211], v[220:223], v[58:61]
	v_mfma_f32_16x16x32_bf16 v[54:57], v[212:215], v[220:223], v[54:57]
	v_mfma_f32_16x16x32_bf16 v[50:53], v[216:219], v[220:223], v[50:53]
	ds_read_b128 v[220:223], v192 offset:12288
	s_waitcnt lgkmcnt(1)
	v_mfma_f32_16x16x32_bf16 v[46:49], v[204:207], v[198:201], v[46:49]
	v_mfma_f32_16x16x32_bf16 v[42:45], v[208:211], v[198:201], v[42:45]
	v_mfma_f32_16x16x32_bf16 v[38:41], v[212:215], v[198:201], v[38:41]
	v_mfma_f32_16x16x32_bf16 v[34:37], v[216:219], v[198:201], v[34:37]
	ds_read_b128 v[198:201], v192 offset:14336
	s_waitcnt lgkmcnt(1)
	v_mfma_f32_16x16x32_bf16 v[30:33], v[204:207], v[220:223], v[30:33]
	v_mfma_f32_16x16x32_bf16 v[26:29], v[208:211], v[220:223], v[26:29]
	v_mfma_f32_16x16x32_bf16 v[22:25], v[212:215], v[220:223], v[22:25]
	v_mfma_f32_16x16x32_bf16 v[18:21], v[216:219], v[220:223], v[18:21]
	s_waitcnt lgkmcnt(0)
	v_mfma_f32_16x16x32_bf16 v[14:17], v[204:207], v[198:201], v[14:17]
	v_mfma_f32_16x16x32_bf16 v[10:13], v[208:211], v[198:201], v[10:13]
	v_mfma_f32_16x16x32_bf16 v[6:9], v[212:215], v[198:201], v[6:9]
	v_mfma_f32_16x16x32_bf16 v[2:5], v[216:219], v[198:201], v[2:5]
	s_cmpk_eq_i32 s2, 0x780
	s_waitcnt vmcnt(0)
	s_barrier
; #define MFMA16(a, b, c) __builtin_amdgcn_mfma_f32_16x16x32_bf16((a), (b), (c), 0, 0, 0)
;     ...
;   for (int kt = 0; kt < nk; ++kt) {
;     const int buf = kt & 1;
;     const char* cA = smem + buf * STAGE + (wm * 32 * MI + r16) * 128;
;     const char* cB = smem + buf * STAGE + 32768 + (wn * 64 + r16) * 128;
; #pragma unroll
;     for (int k2 = 0; k2 < 2; ++k2) {
;       if (k2 == 1 && kt + 1 < nk) STAGE_TILE(buf ^ 1, (kt + 1) * 64)
;       const int po = ((4 * k2 + q4) ^ swz) * 16;
;       bf16x8 bf[4];
; #pragma unroll
;       for (int nt = 0; nt < 4; ++nt) bf[nt] = *(const bf16x8*)(cB + nt * 16 * 128 + po);
;       bf16x8 afc = *(const bf16x8*)(cA + po);
; #pragma unroll
;       for (int a = 0; a < MT; ++a) {
;         bf16x8 afn = afc;
;         if (a + 1 < MT) afn = *(const bf16x8*)(cA + (a + 1) * 16 * 128 + po);
;         __builtin_amdgcn_sched_barrier(0);
; #pragma unroll
;         for (int nt = 0; nt < 4; ++nt) acc[a][nt] = MFMA16(bf[nt], afc, acc[a][nt]);
;         __builtin_amdgcn_sched_barrier(0);
;         afc = afn;
;       }
;     }
;     asm volatile("s_waitcnt vmcnt(0)" ::: "memory");
;     __syncthreads();
;   }
;     ...
;   const int row0 = m0 + wm * 32 * MI + r16, cbw = n0 + wn * 64;
	s_cbranch_scc0 .LBB0_565
	s_add_i32 s2, 0, 0x10000
	v_add_u32_e32 v138, s2, v147
	v_readlane_b32 s2, v254, 18
	s_nop 1
	v_add_u32_e32 v139, s2, v146
	v_add_u32_e32 v144, v139, v145
	ds_read_b128 v[130:133], v144
	ds_read_b128 v[134:137], v144 offset:2048
	ds_read_b128 v[146:149], v144 offset:4096
	ds_read_b128 v[150:153], v144 offset:6144
	v_add_u32_e32 v144, v138, v145
	ds_read_b128 v[154:157], v144
	ds_read_b128 v[158:161], v144 offset:2048
	s_waitcnt lgkmcnt(1)
	v_mfma_f32_16x16x32_bf16 v[122:125], v[134:137], v[154:157], v[122:125]
	v_mfma_f32_16x16x32_bf16 v[118:121], v[146:149], v[154:157], v[118:121]
	v_mfma_f32_16x16x32_bf16 v[114:117], v[150:153], v[154:157], v[114:117]
	v_mfma_f32_16x16x32_bf16 v[126:129], v[130:133], v[154:157], v[126:129]
	ds_read_b128 v[154:157], v144 offset:4096
	s_waitcnt lgkmcnt(1)
	v_mfma_f32_16x16x32_bf16 v[110:113], v[130:133], v[158:161], v[110:113]
	v_mfma_f32_16x16x32_bf16 v[106:109], v[134:137], v[158:161], v[106:109]
	v_mfma_f32_16x16x32_bf16 v[102:105], v[146:149], v[158:161], v[102:105]
	v_mfma_f32_16x16x32_bf16 v[98:101], v[150:153], v[158:161], v[98:101]
	ds_read_b128 v[158:161], v144 offset:6144
	s_waitcnt lgkmcnt(1)
	v_mfma_f32_16x16x32_bf16 v[94:97], v[130:133], v[154:157], v[94:97]
	v_mfma_f32_16x16x32_bf16 v[90:93], v[134:137], v[154:157], v[90:93]
	v_mfma_f32_16x16x32_bf16 v[86:89], v[146:149], v[154:157], v[86:89]
	v_mfma_f32_16x16x32_bf16 v[82:85], v[150:153], v[154:157], v[82:85]
	ds_read_b128 v[154:157], v144 offset:8192
	s_waitcnt lgkmcnt(1)
	v_mfma_f32_16x16x32_bf16 v[78:81], v[130:133], v[158:161], v[78:81]
	v_mfma_f32_16x16x32_bf16 v[74:77], v[134:137], v[158:161], v[74:77]
	v_mfma_f32_16x16x32_bf16 v[70:73], v[146:149], v[158:161], v[70:73]
	v_mfma_f32_16x16x32_bf16 v[66:69], v[150:153], v[158:161], v[66:69]
	ds_read_b128 v[158:161], v144 offset:10240
	s_waitcnt lgkmcnt(1)
	v_mfma_f32_16x16x32_bf16 v[62:65], v[130:133], v[154:157], v[62:65]
	v_mfma_f32_16x16x32_bf16 v[58:61], v[134:137], v[154:157], v[58:61]
	v_mfma_f32_16x16x32_bf16 v[54:57], v[146:149], v[154:157], v[54:57]
	v_mfma_f32_16x16x32_bf16 v[50:53], v[150:153], v[154:157], v[50:53]
	ds_read_b128 v[154:157], v144 offset:12288
	s_waitcnt lgkmcnt(1)
	v_mfma_f32_16x16x32_bf16 v[46:49], v[130:133], v[158:161], v[46:49]
	v_mfma_f32_16x16x32_bf16 v[42:45], v[134:137], v[158:161], v[42:45]
	v_mfma_f32_16x16x32_bf16 v[38:41], v[146:149], v[158:161], v[38:41]
	v_mfma_f32_16x16x32_bf16 v[34:37], v[150:153], v[158:161], v[34:37]
	ds_read_b128 v[158:161], v144 offset:14336
	s_waitcnt lgkmcnt(1)
	v_mfma_f32_16x16x32_bf16 v[30:33], v[130:133], v[154:157], v[30:33]
	v_mfma_f32_16x16x32_bf16 v[26:29], v[134:137], v[154:157], v[26:29]
	v_mfma_f32_16x16x32_bf16 v[22:25], v[146:149], v[154:157], v[22:25]
	v_mfma_f32_16x16x32_bf16 v[18:21], v[150:153], v[154:157], v[18:21]
	s_waitcnt lgkmcnt(0)
	v_mfma_f32_16x16x32_bf16 v[14:17], v[130:133], v[158:161], v[14:17]
	v_mfma_f32_16x16x32_bf16 v[10:13], v[134:137], v[158:161], v[10:13]
	v_mfma_f32_16x16x32_bf16 v[6:9], v[146:149], v[158:161], v[6:9]
	v_mfma_f32_16x16x32_bf16 v[2:5], v[150:153], v[158:161], v[2:5]
	v_add_u32_e32 v130, v139, v143
	ds_read_b128 v[134:137], v130
	ds_read_b128 v[144:147], v130 offset:2048
	ds_read_b128 v[148:151], v130 offset:4096
	ds_read_b128 v[152:155], v130 offset:6144
	v_add_u32_e32 v138, v138, v143
	ds_read_b128 v[156:159], v138
	ds_read_b128 v[164:167], v138 offset:2048
	s_waitcnt lgkmcnt(1)
	v_mfma_f32_16x16x32_bf16 v[130:133], v[134:137], v[156:159], v[126:129]
	v_mfma_f32_16x16x32_bf16 v[122:125], v[144:147], v[156:159], v[122:125]
	v_mfma_f32_16x16x32_bf16 v[118:121], v[148:151], v[156:159], v[118:121]
	v_mfma_f32_16x16x32_bf16 v[114:117], v[152:155], v[156:159], v[114:117]
	ds_read_b128 v[126:129], v138 offset:4096
	s_waitcnt lgkmcnt(1)
	v_mfma_f32_16x16x32_bf16 v[110:113], v[134:137], v[164:167], v[110:113]
	v_mfma_f32_16x16x32_bf16 v[106:109], v[144:147], v[164:167], v[106:109]
	v_mfma_f32_16x16x32_bf16 v[102:105], v[148:151], v[164:167], v[102:105]
	v_mfma_f32_16x16x32_bf16 v[98:101], v[152:155], v[164:167], v[98:101]
	ds_read_b128 v[156:159], v138 offset:6144
	s_waitcnt lgkmcnt(1)
	v_mfma_f32_16x16x32_bf16 v[94:97], v[134:137], v[126:129], v[94:97]
	v_mfma_f32_16x16x32_bf16 v[90:93], v[144:147], v[126:129], v[90:93]
	v_mfma_f32_16x16x32_bf16 v[86:89], v[148:151], v[126:129], v[86:89]
	v_mfma_f32_16x16x32_bf16 v[82:85], v[152:155], v[126:129], v[82:85]
	ds_read_b128 v[126:129], v138 offset:8192
	s_waitcnt lgkmcnt(1)
	v_mfma_f32_16x16x32_bf16 v[78:81], v[134:137], v[156:159], v[78:81]
	v_mfma_f32_16x16x32_bf16 v[74:77], v[144:147], v[156:159], v[74:77]
	v_mfma_f32_16x16x32_bf16 v[70:73], v[148:151], v[156:159], v[70:73]
	v_mfma_f32_16x16x32_bf16 v[66:69], v[152:155], v[156:159], v[66:69]
	ds_read_b128 v[156:159], v138 offset:10240
	s_waitcnt lgkmcnt(1)
	v_mfma_f32_16x16x32_bf16 v[62:65], v[134:137], v[126:129], v[62:65]
	v_mfma_f32_16x16x32_bf16 v[58:61], v[144:147], v[126:129], v[58:61]
	v_mfma_f32_16x16x32_bf16 v[54:57], v[148:151], v[126:129], v[54:57]
	v_mfma_f32_16x16x32_bf16 v[50:53], v[152:155], v[126:129], v[50:53]
	ds_read_b128 v[126:129], v138 offset:12288
	s_waitcnt lgkmcnt(1)
	v_mfma_f32_16x16x32_bf16 v[46:49], v[134:137], v[156:159], v[46:49]
	v_mfma_f32_16x16x32_bf16 v[42:45], v[144:147], v[156:159], v[42:45]
	v_mfma_f32_16x16x32_bf16 v[38:41], v[148:151], v[156:159], v[38:41]
	v_mfma_f32_16x16x32_bf16 v[34:37], v[152:155], v[156:159], v[34:37]
	ds_read_b128 v[156:159], v138 offset:14336
	s_waitcnt lgkmcnt(1)
	v_mfma_f32_16x16x32_bf16 v[30:33], v[134:137], v[126:129], v[30:33]
	v_mfma_f32_16x16x32_bf16 v[26:29], v[144:147], v[126:129], v[26:29]
	v_mfma_f32_16x16x32_bf16 v[22:25], v[148:151], v[126:129], v[22:25]
	v_mfma_f32_16x16x32_bf16 v[18:21], v[152:155], v[126:129], v[18:21]
	s_waitcnt lgkmcnt(0)
	v_mfma_f32_16x16x32_bf16 v[14:17], v[134:137], v[156:159], v[14:17]
	v_mfma_f32_16x16x32_bf16 v[10:13], v[144:147], v[156:159], v[10:13]
	v_mfma_f32_16x16x32_bf16 v[6:9], v[148:151], v[156:159], v[6:9]
	v_mfma_f32_16x16x32_bf16 v[2:5], v[152:155], v[156:159], v[2:5]
	s_waitcnt vmcnt(0)
	v_lshl_or_b32 v190, v142, 6, s22
	s_movk_i32 s2, 0x981
	v_cmp_gt_i32_e32 vcc, s2, v190
	s_barrier
; DI bf16_t f2bf(float x) { return (bf16_t)(pack2(x, 0.f) & 0xffffu); }
; DI void phase_win(char* smem, const Params& p, int layer) {
;     ...
;   auto ep = [&](int row, int cbw, int q4, const f32x4& c0, const f32x4& c1, const f32x4& c2, const f32x4& c3) {
;     if (cbw > 2432) return;
;     const int b = row / TT, t = row - b * TT;
;     const bool lat = t >= CTXL;
;     const int pos = t - CTXL;
;     float v[16] = {c0[0], c0[1], c0[2], c0[3], c1[0], c1[1], c1[2], c1[3], c2[0], c2[1], c2[2], c2[3], c3[0], c3[1], c3[2], c3[3]};
;     if (cbw >= 640 && cbw < 768) {
;       bf16_t* vp = p.VsT + ((size_t)(b * 2 + ((cbw - 640) >> 6)) * 64 + q4 * 16) * TT + t;
; #pragma unroll
;       for (int i = 0; i < 16; ++i) vp[(size_t)i * TT] = f2bf(v[i]);
;       return;
;     }
;     const bool r16 = cbw >= 256 && cbw < 640, rkr = cbw == 2432;
;     if (rkr && q4 >= 2) return;
;     if (lat && (r16 || rkr)) {
;       const int a = r16 ? (q4 >> 1) : q4;
;       const int pa = a ? (pos & 63) : (pos >> 6);
;       const float* tab = r16 ? p.ropeS + 2 * (pa * 16 + (q4 & 1) * 8) : p.ropeM + 2 * (pa * 8);
; #pragma unroll
;       for (int k = 0; k < 4; ++k) {
;         const float4 cs = *(const float4*)(tab + 4 * k);
;         const float x0 = v[4 * k], x1 = v[4 * k + 1], x2 = v[4 * k + 2], x3 = v[4 * k + 3];
;         v[4 * k] = x0 * cs.x - x1 * cs.y; v[4 * k + 1] = x1 * cs.x + x0 * cs.y;
;         v[4 * k + 2] = x2 * cs.z - x3 * cs.w; v[4 * k + 3] = x3 * cs.z + x2 * cs.w;
;       }
;     }
	s_and_saveexec_b64 s[96:97], vcc
	s_cbranch_execz .LBB0_557
	v_or_b32_e32 v126, s4, v162
	v_lshl_add_u32 v136, v141, 7, v126
	v_and_b32_e32 v126, 0xffffff80, v190
	s_movk_i32 s2, 0x280
	v_cmp_ne_u32_e64 s[16:17], s2, v126
	s_movk_i32 s2, 0x27f
	v_cmp_lt_i32_e64 s[4:5], s2, v190
	s_movk_i32 s2, 0x980
	v_cmp_ne_u32_e64 s[8:9], s2, v190
	v_cmp_gt_u32_e64 s[6:7], 2, v140
	v_add_u32_e32 v126, 0xffffff00, v190
	v_cmp_eq_u32_e32 vcc, s2, v190
	s_or_b64 s[2:3], s[8:9], s[6:7]
	s_movk_i32 s6, 0x180
	v_cmp_gt_u32_e64 s[12:13], s6, v126
	s_or_b64 s[86:87], vcc, s[12:13]
	v_lshrrev_b32_e32 v160, 6, v126
	v_cndmask_b32_e64 v127, 0, 1, s[12:13]
	v_lshrrev_b32_e32 v127, v127, v140
	v_cmp_eq_u32_e64 s[14:15], 0, v127
	v_add_u32_e32 v127, 0xfffffe00, v190
	v_mul_hi_i32 v126, v136, s1
	s_cmp_eq_u32 s10, 1
	v_lshrrev_b32_e32 v159, 6, v127
	v_lshrrev_b32_e32 v127, 31, v126
	v_ashrrev_i32_e32 v126, 11, v126
	v_lshlrev_b32_e32 v158, 4, v140
	s_movk_i32 s6, 0x1ff
	s_cselect_b64 s[94:95], -1, 0
	s_movk_i32 s10, 0xff
	s_cmpk_gt_u32 s22, 0x7ff
	v_add_u32_e32 v139, v126, v127
	v_and_b32_e32 v161, 16, v158
	v_cmp_lt_i32_e64 s[6:7], s6, v190
	v_cmp_lt_i32_e64 s[10:11], s10, v190
	s_cselect_b64 s[22:23], -1, 0
	v_ashrrev_i32_e32 v135, 31, v190
	v_mov_b32_e32 v134, v190
	v_mad_i32_i24 v138, v139, s80, v136
	s_and_saveexec_b64 s[30:31], s[16:17]
	s_xor_b64 s[30:31], exec, s[30:31]
	s_cbranch_execz .LBB0_594
	s_and_saveexec_b64 s[52:53], s[2:3]
	s_cbranch_execz .LBB0_593
	s_movk_i32 s45, 0xff
	v_cmp_lt_i32_e32 vcc, s45, v138
	s_and_b64 s[46:47], s[86:87], vcc
	v_mov_b32_e32 v140, v131
	v_mov_b32_e32 v141, v133
	v_mov_b32_e32 v142, v123
	v_mov_b32_e32 v143, v125
	v_mov_b32_e32 v144, v119
	v_mov_b32_e32 v145, v121
	v_mov_b32_e32 v154, v115
	v_mov_b32_e32 v155, v117
	v_mov_b32_e32 v146, v130
	v_mov_b32_e32 v147, v132
	v_mov_b32_e32 v148, v122
	v_mov_b32_e32 v149, v124
	v_mov_b32_e32 v150, v118
	v_mov_b32_e32 v151, v120
	v_mov_b32_e32 v152, v114
	v_mov_b32_e32 v153, v116
	s_and_saveexec_b64 s[54:55], s[46:47]
	s_cbranch_execz .LBB0_571
	v_readlane_b32 s46, v252, 1
	v_cndmask_b32_e64 v128, v238, v240, s[12:13]
	v_mov_b32_e32 v129, v191
	v_readlane_b32 s47, v252, 2
	v_add_u32_e32 v126, 0xffffff00, v138
	v_lshrrev_b32_e32 v126, 6, v126
	v_lshl_add_u64 v[128:129], s[46:47], 0, v[128:129]
	global_load_dwordx2 v[128:129], v[128:129], off
	v_cndmask_b32_e64 v126, v162, v126, s[14:15]
	v_lshlrev_b32_e32 v127, 4, v126
	v_lshl_or_b32 v126, v126, 5, v161
	v_cndmask_b32_e64 v126, v127, v126, s[12:13]
	v_mov_b32_e32 v127, v191
	v_mov_b32_e32 v182, v130
	v_mov_b32_e32 v183, v133
	v_mov_b32_e32 v130, v131
	v_mov_b32_e32 v131, v132
	s_waitcnt vmcnt(0)
	v_lshl_add_u64 v[156:157], v[126:127], 2, v[128:129]
	global_load_dwordx4 v[126:129], v[156:157], off offset:48
	global_load_dwordx4 v[164:167], v[156:157], off offset:32
	global_load_dwordx4 v[168:171], v[156:157], off offset:16
	global_load_dwordx4 v[172:175], v[156:157], off
	s_waitcnt vmcnt(3)
	v_mov_b32_e32 v156, v127
	s_waitcnt vmcnt(2)
	v_mov_b32_e32 v180, v165
	s_waitcnt vmcnt(1)
	v_mov_b32_e32 v178, v169
	s_waitcnt vmcnt(0)
	v_mov_b32_e32 v132, v172
	v_mov_b32_e32 v133, v175
	v_mov_b32_e32 v176, v173
	v_mov_b32_e32 v177, v174
	v_pk_mul_f32 v[130:131], v[130:131], v[132:133]
	v_mov_b32_e32 v132, v173
	v_pk_mul_f32 v[132:133], v[140:141], v[132:133]
	v_pk_fma_f32 v[140:141], v[182:183], v[176:177], v[130:131]
	v_mov_b32_e32 v130, v122
	v_mov_b32_e32 v131, v125
	v_mov_b32_e32 v122, v123
	v_mov_b32_e32 v123, v124
	v_mov_b32_e32 v124, v168
	v_mov_b32_e32 v125, v171
	v_mov_b32_e32 v179, v170
	v_pk_mul_f32 v[122:123], v[122:123], v[124:125]
	v_mov_b32_e32 v124, v169
	v_pk_mul_f32 v[124:125], v[142:143], v[124:125]
	v_pk_fma_f32 v[142:143], v[130:131], v[178:179], v[122:123]
	v_mov_b32_e32 v122, v118
	v_mov_b32_e32 v123, v121
	v_mov_b32_e32 v118, v119
	v_mov_b32_e32 v119, v120
	v_mov_b32_e32 v120, v164
	v_mov_b32_e32 v121, v167
	v_mov_b32_e32 v181, v166
	v_pk_mul_f32 v[118:119], v[118:119], v[120:121]
	v_mov_b32_e32 v120, v165
	v_pk_mul_f32 v[120:121], v[144:145], v[120:121]
	v_pk_fma_f32 v[144:145], v[122:123], v[180:181], v[118:119]
	v_mov_b32_e32 v118, v114
	v_mov_b32_e32 v119, v117
	v_mov_b32_e32 v114, v115
	v_mov_b32_e32 v115, v116
	v_mov_b32_e32 v116, v126
	v_mov_b32_e32 v117, v129
	v_pk_mul_f32 v[114:115], v[114:115], v[116:117]
	v_mov_b32_e32 v116, v127
	v_mov_b32_e32 v157, v128
	v_mov_b32_e32 v173, v174
	v_mov_b32_e32 v169, v170
	v_mov_b32_e32 v165, v166
	v_pk_mul_f32 v[116:117], v[154:155], v[116:117]
	v_mov_b32_e32 v127, v128
	v_pk_fma_f32 v[146:147], v[146:147], v[172:173], v[132:133] neg_lo:[0,0,1] neg_hi:[0,0,1]
	v_pk_fma_f32 v[148:149], v[148:149], v[168:169], v[124:125] neg_lo:[0,0,1] neg_hi:[0,0,1]
	v_pk_fma_f32 v[150:151], v[150:151], v[164:165], v[120:121] neg_lo:[0,0,1] neg_hi:[0,0,1]
	v_pk_fma_f32 v[152:153], v[152:153], v[126:127], v[116:117] neg_lo:[0,0,1] neg_hi:[0,0,1]
	v_pk_fma_f32 v[154:155], v[118:119], v[156:157], v[114:115]
